# v66 + the s_setprio 0 / s_setprio 1 toggle in the middle of each MFMA phase removed (6 large K-loops)
# speedup vs baseline: 1.0070x; 1.0070x over previous
.LBB0_162:
	ds_read_b128 v[154:157], v151
	ds_read_b128 v[158:161], v151 offset:1024
	ds_read_b128 v[162:165], v151 offset:2048
	ds_read_b128 v[166:169], v151 offset:3072
	ds_read_b128 v[170:173], v152
	ds_read_b128 v[174:177], v152 offset:1024
	ds_read_b128 v[178:181], v152 offset:2048
	ds_read_b128 v[182:185], v152 offset:3072
	s_add_u32 s58, s40, 0xfff00080
	s_addc_u32 s59, s41, -1
	s_cmp_eq_u32 s73, 60
	s_cselect_b32 s63, s25, s59
	s_cselect_b32 s62, s67, s58
	s_cselect_b32 s59, s23, s72
	s_cselect_b32 s58, s70, s71
	v_lshl_add_u64 v[146:147], s[40:41], 0, v[138:139]
	s_add_i32 m0, s42, 0xc000
	ds_read_b128 v[186:189], v153
	ds_read_b128 v[190:193], v153 offset:1024
	ds_read_b128 v[194:197], v153 offset:2048
	ds_read_b128 v[198:201], v153 offset:3072
	ds_read_b128 v[202:205], v153 offset:4096
	ds_read_b128 v[206:209], v153 offset:5120
	ds_read_b128 v[210:213], v153 offset:6144
	ds_read_b128 v[214:217], v153 offset:7168
	global_load_lds_dwordx4 v[146:147], off
	v_lshl_add_u64 v[146:147], s[40:41], 0, v[140:141]
	s_add_i32 m0, s42, 0xe000
	s_nop 0
	global_load_lds_dwordx4 v[146:147], off
	s_waitcnt vmcnt(8)
	s_waitcnt lgkmcnt(0)
	s_barrier
	s_setprio 1
	s_waitcnt lgkmcnt(0)
	v_mfma_f32_16x16x32_bf16 v[126:129], v[154:157], v[186:189], v[126:129]
	v_mfma_f32_16x16x32_bf16 v[118:121], v[162:165], v[186:189], v[118:121]
	v_mfma_f32_16x16x32_bf16 v[110:113], v[154:157], v[194:197], v[110:113]
	v_mfma_f32_16x16x32_bf16 v[102:105], v[162:165], v[194:197], v[102:105]
	v_mfma_f32_16x16x32_bf16 v[94:97], v[154:157], v[202:205], v[94:97]
	v_mfma_f32_16x16x32_bf16 v[86:89], v[162:165], v[202:205], v[86:89]
	v_mfma_f32_16x16x32_bf16 v[78:81], v[154:157], v[210:213], v[78:81]
	v_mfma_f32_16x16x32_bf16 v[70:73], v[162:165], v[210:213], v[70:73]
	v_mfma_f32_16x16x32_bf16 v[126:129], v[158:161], v[190:193], v[126:129]
	v_mfma_f32_16x16x32_bf16 v[118:121], v[166:169], v[190:193], v[118:121]
	v_mfma_f32_16x16x32_bf16 v[110:113], v[158:161], v[198:201], v[110:113]
	v_mfma_f32_16x16x32_bf16 v[102:105], v[166:169], v[198:201], v[102:105]
	v_mfma_f32_16x16x32_bf16 v[94:97], v[158:161], v[206:209], v[94:97]
	v_mfma_f32_16x16x32_bf16 v[86:89], v[166:169], v[206:209], v[86:89]
	v_mfma_f32_16x16x32_bf16 v[78:81], v[158:161], v[214:217], v[78:81]
	v_mfma_f32_16x16x32_bf16 v[70:73], v[166:169], v[214:217], v[70:73]
	v_mfma_f32_16x16x32_bf16 v[122:125], v[170:173], v[186:189], v[122:125]
	v_mfma_f32_16x16x32_bf16 v[114:117], v[178:181], v[186:189], v[114:117]
	v_mfma_f32_16x16x32_bf16 v[106:109], v[170:173], v[194:197], v[106:109]
	v_mfma_f32_16x16x32_bf16 v[98:101], v[178:181], v[194:197], v[98:101]
	v_mfma_f32_16x16x32_bf16 v[90:93], v[170:173], v[202:205], v[90:93]
	v_mfma_f32_16x16x32_bf16 v[82:85], v[178:181], v[202:205], v[82:85]
	v_mfma_f32_16x16x32_bf16 v[74:77], v[170:173], v[210:213], v[74:77]
	v_mfma_f32_16x16x32_bf16 v[66:69], v[178:181], v[210:213], v[66:69]
	v_mfma_f32_16x16x32_bf16 v[122:125], v[174:177], v[190:193], v[122:125]
	v_mfma_f32_16x16x32_bf16 v[114:117], v[182:185], v[190:193], v[114:117]
	v_mfma_f32_16x16x32_bf16 v[106:109], v[174:177], v[198:201], v[106:109]
	v_mfma_f32_16x16x32_bf16 v[98:101], v[182:185], v[198:201], v[98:101]
	v_mfma_f32_16x16x32_bf16 v[90:93], v[174:177], v[206:209], v[90:93]
	v_mfma_f32_16x16x32_bf16 v[82:85], v[182:185], v[206:209], v[82:85]
	v_mfma_f32_16x16x32_bf16 v[74:77], v[174:177], v[214:217], v[74:77]
	v_mfma_f32_16x16x32_bf16 v[66:69], v[182:185], v[214:217], v[66:69]
	s_setprio 0
	s_barrier
	s_add_i32 s74, s50, s15
	v_lshl_add_u64 v[146:147], s[58:59], 0, v[134:135]
	s_mov_b32 m0, s74
	ds_read_b128 v[186:189], v153 offset:16384
	ds_read_b128 v[190:193], v153 offset:17408
	ds_read_b128 v[194:197], v153 offset:18432
	ds_read_b128 v[198:201], v153 offset:19456
	ds_read_b128 v[202:205], v153 offset:20480
	ds_read_b128 v[206:209], v153 offset:21504
	ds_read_b128 v[210:213], v153 offset:22528
	ds_read_b128 v[214:217], v153 offset:23552
	global_load_lds_dwordx4 v[146:147], off
	s_add_i32 m0, s74, 0x2000
	s_add_u32 s74, s58, 0x100000
	v_lshl_add_u64 v[218:219], s[58:59], 0, v[130:131]
	s_addc_u32 s75, s59, 0
	s_add_i32 s82, s51, s15
	global_load_lds_dwordx4 v[218:219], off
	v_lshl_add_u64 v[220:221], s[74:75], 0, v[134:135]
	s_mov_b32 m0, s82
	v_lshl_add_u64 v[222:223], s[62:63], 0, v[132:133]
	global_load_lds_dwordx4 v[220:221], off
	v_lshl_add_u64 v[220:221], s[74:75], 0, v[130:131]
	s_add_i32 m0, s82, 0x2000
	s_nop 0
	global_load_lds_dwordx4 v[220:221], off
	v_lshl_add_u64 v[220:221], s[62:63], 0, v[136:137]
	s_mov_b32 m0, s42
	s_nop 0
	global_load_lds_dwordx4 v[220:221], off
	s_mov_b32 m0, s43
	s_nop 0
	global_load_lds_dwordx4 v[222:223], off
	s_waitcnt vmcnt(8)
	s_waitcnt lgkmcnt(0)
	s_barrier
	s_setprio 1
	s_waitcnt lgkmcnt(0)
	v_mfma_f32_16x16x32_bf16 v[62:65], v[154:157], v[186:189], v[62:65]
	v_mfma_f32_16x16x32_bf16 v[54:57], v[162:165], v[186:189], v[54:57]
	v_mfma_f32_16x16x32_bf16 v[46:49], v[154:157], v[194:197], v[46:49]
	v_mfma_f32_16x16x32_bf16 v[38:41], v[162:165], v[194:197], v[38:41]
	v_mfma_f32_16x16x32_bf16 v[30:33], v[154:157], v[202:205], v[30:33]
	v_mfma_f32_16x16x32_bf16 v[22:25], v[162:165], v[202:205], v[22:25]
	v_mfma_f32_16x16x32_bf16 v[14:17], v[154:157], v[210:213], v[14:17]
	v_mfma_f32_16x16x32_bf16 v[6:9], v[162:165], v[210:213], v[6:9]
	v_mfma_f32_16x16x32_bf16 v[62:65], v[158:161], v[190:193], v[62:65]
	v_mfma_f32_16x16x32_bf16 v[54:57], v[166:169], v[190:193], v[54:57]
	v_mfma_f32_16x16x32_bf16 v[46:49], v[158:161], v[198:201], v[46:49]
	v_mfma_f32_16x16x32_bf16 v[38:41], v[166:169], v[198:201], v[38:41]
	v_mfma_f32_16x16x32_bf16 v[30:33], v[158:161], v[206:209], v[30:33]
	v_mfma_f32_16x16x32_bf16 v[22:25], v[166:169], v[206:209], v[22:25]
	v_mfma_f32_16x16x32_bf16 v[14:17], v[158:161], v[214:217], v[14:17]
	v_mfma_f32_16x16x32_bf16 v[6:9], v[166:169], v[214:217], v[6:9]
	v_mfma_f32_16x16x32_bf16 v[58:61], v[170:173], v[186:189], v[58:61]
	v_mfma_f32_16x16x32_bf16 v[50:53], v[178:181], v[186:189], v[50:53]
	v_mfma_f32_16x16x32_bf16 v[42:45], v[170:173], v[194:197], v[42:45]
	v_mfma_f32_16x16x32_bf16 v[34:37], v[178:181], v[194:197], v[34:37]
	v_mfma_f32_16x16x32_bf16 v[26:29], v[170:173], v[202:205], v[26:29]
	v_mfma_f32_16x16x32_bf16 v[18:21], v[178:181], v[202:205], v[18:21]
	v_mfma_f32_16x16x32_bf16 v[10:13], v[170:173], v[210:213], v[10:13]
	v_mfma_f32_16x16x32_bf16 v[2:5], v[178:181], v[210:213], v[2:5]
	v_mfma_f32_16x16x32_bf16 v[58:61], v[174:177], v[190:193], v[58:61]
	v_mfma_f32_16x16x32_bf16 v[50:53], v[182:185], v[190:193], v[50:53]
	v_mfma_f32_16x16x32_bf16 v[42:45], v[174:177], v[198:201], v[42:45]
	v_mfma_f32_16x16x32_bf16 v[34:37], v[182:185], v[198:201], v[34:37]
	v_mfma_f32_16x16x32_bf16 v[26:29], v[174:177], v[206:209], v[26:29]
	v_mfma_f32_16x16x32_bf16 v[18:21], v[182:185], v[206:209], v[18:21]
	v_mfma_f32_16x16x32_bf16 v[10:13], v[174:177], v[214:217], v[10:13]
	v_mfma_f32_16x16x32_bf16 v[2:5], v[182:185], v[214:217], v[2:5]
	s_setprio 0
	s_barrier
	s_add_i32 s74, 0, 0x18000
	s_add_i32 s75, 0, 0x1c000
	v_add_u32_e32 v166, s74, v149
	v_add_u32_e32 v182, s75, v149
	ds_read_b128 v[154:157], v166
	ds_read_b128 v[158:161], v166 offset:1024
	ds_read_b128 v[162:165], v166 offset:2048
	ds_read_b128 v[166:169], v166 offset:3072
	ds_read_b128 v[170:173], v182
	ds_read_b128 v[174:177], v182 offset:1024
	ds_read_b128 v[178:181], v182 offset:2048
	ds_read_b128 v[182:185], v182 offset:3072
	s_add_u32 s62, s62, 0x100000
	s_addc_u32 s63, s63, 0
	s_mov_b32 m0, s44
	v_lshl_add_u64 v[224:225], s[62:63], 0, v[136:137]
	ds_read_b128 v[186:189], v153 offset:32768
	ds_read_b128 v[190:193], v153 offset:33792
	ds_read_b128 v[194:197], v153 offset:34816
	ds_read_b128 v[198:201], v153 offset:35840
	ds_read_b128 v[202:205], v153 offset:36864
	ds_read_b128 v[206:209], v153 offset:37888
	ds_read_b128 v[210:213], v153 offset:38912
	ds_read_b128 v[214:217], v153 offset:39936
	global_load_lds_dwordx4 v[224:225], off
	v_lshl_add_u64 v[224:225], s[62:63], 0, v[132:133]
	s_mov_b32 m0, s45
	s_nop 0
	global_load_lds_dwordx4 v[224:225], off
	s_waitcnt vmcnt(8)
	s_waitcnt lgkmcnt(0)
	s_barrier
	s_setprio 1
	s_waitcnt lgkmcnt(0)
	v_mfma_f32_16x16x32_bf16 v[126:129], v[154:157], v[186:189], v[126:129]
	v_mfma_f32_16x16x32_bf16 v[118:121], v[162:165], v[186:189], v[118:121]
	v_mfma_f32_16x16x32_bf16 v[110:113], v[154:157], v[194:197], v[110:113]
	v_mfma_f32_16x16x32_bf16 v[102:105], v[162:165], v[194:197], v[102:105]
	v_mfma_f32_16x16x32_bf16 v[94:97], v[154:157], v[202:205], v[94:97]
	v_mfma_f32_16x16x32_bf16 v[86:89], v[162:165], v[202:205], v[86:89]
	v_mfma_f32_16x16x32_bf16 v[78:81], v[154:157], v[210:213], v[78:81]
	v_mfma_f32_16x16x32_bf16 v[70:73], v[162:165], v[210:213], v[70:73]
	v_mfma_f32_16x16x32_bf16 v[126:129], v[158:161], v[190:193], v[126:129]
	v_mfma_f32_16x16x32_bf16 v[118:121], v[166:169], v[190:193], v[118:121]
	v_mfma_f32_16x16x32_bf16 v[110:113], v[158:161], v[198:201], v[110:113]
	v_mfma_f32_16x16x32_bf16 v[102:105], v[166:169], v[198:201], v[102:105]
	v_mfma_f32_16x16x32_bf16 v[94:97], v[158:161], v[206:209], v[94:97]
	v_mfma_f32_16x16x32_bf16 v[86:89], v[166:169], v[206:209], v[86:89]
	v_mfma_f32_16x16x32_bf16 v[78:81], v[158:161], v[214:217], v[78:81]
	v_mfma_f32_16x16x32_bf16 v[70:73], v[166:169], v[214:217], v[70:73]
	v_mfma_f32_16x16x32_bf16 v[122:125], v[170:173], v[186:189], v[122:125]
	v_mfma_f32_16x16x32_bf16 v[114:117], v[178:181], v[186:189], v[114:117]
	v_mfma_f32_16x16x32_bf16 v[106:109], v[170:173], v[194:197], v[106:109]
	v_mfma_f32_16x16x32_bf16 v[98:101], v[178:181], v[194:197], v[98:101]
	v_mfma_f32_16x16x32_bf16 v[90:93], v[170:173], v[202:205], v[90:93]
	v_mfma_f32_16x16x32_bf16 v[82:85], v[178:181], v[202:205], v[82:85]
	v_mfma_f32_16x16x32_bf16 v[74:77], v[170:173], v[210:213], v[74:77]
	v_mfma_f32_16x16x32_bf16 v[66:69], v[178:181], v[210:213], v[66:69]
	v_mfma_f32_16x16x32_bf16 v[122:125], v[174:177], v[190:193], v[122:125]
	v_mfma_f32_16x16x32_bf16 v[114:117], v[182:185], v[190:193], v[114:117]
	v_mfma_f32_16x16x32_bf16 v[106:109], v[174:177], v[198:201], v[106:109]
	v_mfma_f32_16x16x32_bf16 v[98:101], v[182:185], v[198:201], v[98:101]
	v_mfma_f32_16x16x32_bf16 v[90:93], v[174:177], v[206:209], v[90:93]
	v_mfma_f32_16x16x32_bf16 v[82:85], v[182:185], v[206:209], v[82:85]
	v_mfma_f32_16x16x32_bf16 v[74:77], v[174:177], v[214:217], v[74:77]
	v_mfma_f32_16x16x32_bf16 v[66:69], v[182:185], v[214:217], v[66:69]
	s_setprio 0
	s_barrier
	s_add_i32 s62, s74, s15
	v_lshl_add_u64 v[146:147], v[146:147], 0, s[10:11]
	s_mov_b32 m0, s62
	ds_read_b128 v[186:189], v153 offset:49152
	ds_read_b128 v[190:193], v153 offset:50176
	ds_read_b128 v[194:197], v153 offset:51200
	ds_read_b128 v[198:201], v153 offset:52224
	ds_read_b128 v[202:205], v153 offset:53248
	ds_read_b128 v[206:209], v153 offset:54272
	ds_read_b128 v[210:213], v153 offset:55296
	ds_read_b128 v[214:217], v153 offset:56320
	global_load_lds_dwordx4 v[146:147], off
	s_add_i32 m0, s62, 0x2000
	s_add_u32 s58, s58, 0x100080
	v_lshl_add_u64 v[146:147], v[218:219], 0, s[10:11]
	s_addc_u32 s59, s59, 0
	s_add_i32 s62, s75, s15
	global_load_lds_dwordx4 v[146:147], off
	v_lshl_add_u64 v[146:147], s[58:59], 0, v[134:135]
	s_mov_b32 m0, s62
	s_nop 0
	global_load_lds_dwordx4 v[146:147], off
	v_lshl_add_u64 v[146:147], s[58:59], 0, v[130:131]
	s_add_i32 m0, s62, 0x2000
	s_nop 0
	global_load_lds_dwordx4 v[146:147], off
	v_lshl_add_u64 v[146:147], v[220:221], 0, s[10:11]
	s_mov_b32 m0, s47
	s_nop 0
	global_load_lds_dwordx4 v[146:147], off
	v_lshl_add_u64 v[146:147], v[222:223], 0, s[10:11]
	s_mov_b32 m0, s48
	s_nop 0
	global_load_lds_dwordx4 v[146:147], off
	s_waitcnt vmcnt(8)
	s_waitcnt lgkmcnt(0)
	s_barrier
	s_setprio 1
	s_waitcnt lgkmcnt(0)
	v_mfma_f32_16x16x32_bf16 v[62:65], v[154:157], v[186:189], v[62:65]
	v_mfma_f32_16x16x32_bf16 v[54:57], v[162:165], v[186:189], v[54:57]
	v_mfma_f32_16x16x32_bf16 v[46:49], v[154:157], v[194:197], v[46:49]
	v_mfma_f32_16x16x32_bf16 v[38:41], v[162:165], v[194:197], v[38:41]
	v_mfma_f32_16x16x32_bf16 v[30:33], v[154:157], v[202:205], v[30:33]
	v_mfma_f32_16x16x32_bf16 v[22:25], v[162:165], v[202:205], v[22:25]
	v_mfma_f32_16x16x32_bf16 v[14:17], v[154:157], v[210:213], v[14:17]
	v_mfma_f32_16x16x32_bf16 v[6:9], v[162:165], v[210:213], v[6:9]
	v_mfma_f32_16x16x32_bf16 v[62:65], v[158:161], v[190:193], v[62:65]
	v_mfma_f32_16x16x32_bf16 v[54:57], v[166:169], v[190:193], v[54:57]
	v_mfma_f32_16x16x32_bf16 v[46:49], v[158:161], v[198:201], v[46:49]
	v_mfma_f32_16x16x32_bf16 v[38:41], v[166:169], v[198:201], v[38:41]
	v_mfma_f32_16x16x32_bf16 v[30:33], v[158:161], v[206:209], v[30:33]
	v_mfma_f32_16x16x32_bf16 v[22:25], v[166:169], v[206:209], v[22:25]
	v_mfma_f32_16x16x32_bf16 v[14:17], v[158:161], v[214:217], v[14:17]
	v_mfma_f32_16x16x32_bf16 v[6:9], v[166:169], v[214:217], v[6:9]
	v_mfma_f32_16x16x32_bf16 v[58:61], v[170:173], v[186:189], v[58:61]
	v_mfma_f32_16x16x32_bf16 v[50:53], v[178:181], v[186:189], v[50:53]
	v_mfma_f32_16x16x32_bf16 v[42:45], v[170:173], v[194:197], v[42:45]
	v_mfma_f32_16x16x32_bf16 v[34:37], v[178:181], v[194:197], v[34:37]
	v_mfma_f32_16x16x32_bf16 v[26:29], v[170:173], v[202:205], v[26:29]
	v_mfma_f32_16x16x32_bf16 v[18:21], v[178:181], v[202:205], v[18:21]
	v_mfma_f32_16x16x32_bf16 v[10:13], v[170:173], v[210:213], v[10:13]
	v_mfma_f32_16x16x32_bf16 v[2:5], v[178:181], v[210:213], v[2:5]
	v_mfma_f32_16x16x32_bf16 v[58:61], v[174:177], v[190:193], v[58:61]
	v_mfma_f32_16x16x32_bf16 v[50:53], v[182:185], v[190:193], v[50:53]
	v_mfma_f32_16x16x32_bf16 v[42:45], v[174:177], v[198:201], v[42:45]
	v_mfma_f32_16x16x32_bf16 v[34:37], v[182:185], v[198:201], v[34:37]
	v_mfma_f32_16x16x32_bf16 v[26:29], v[174:177], v[206:209], v[26:29]
	v_mfma_f32_16x16x32_bf16 v[18:21], v[182:185], v[206:209], v[18:21]
	v_mfma_f32_16x16x32_bf16 v[10:13], v[174:177], v[214:217], v[10:13]
	v_mfma_f32_16x16x32_bf16 v[2:5], v[182:185], v[214:217], v[2:5]
	s_setprio 0
	s_barrier
	s_add_i32 s73, s73, 2
	s_add_u32 s40, s40, 0x100
	s_addc_u32 s41, s41, 0
	s_add_u32 s71, s71, 0x100
	s_addc_u32 s72, s72, 0
	s_cmp_gt_u32 s73, 61
	s_cbranch_scc0 .LBB0_162
	s_and_b64 vcc, exec, s[12:13]
	s_cbranch_vccz .LBB0_165
	s_barrier

.LBB0_260:
	ds_read_b128 v[154:157], v150
	ds_read_b128 v[158:161], v150 offset:1024
	ds_read_b128 v[162:165], v150 offset:2048
	ds_read_b128 v[166:169], v150 offset:3072
	ds_read_b128 v[170:173], v151
	ds_read_b128 v[174:177], v151 offset:1024
	ds_read_b128 v[178:181], v151 offset:2048
	ds_read_b128 v[182:185], v151 offset:3072
	s_add_u32 s30, s28, 0x100
	s_addc_u32 s31, s29, 0
	s_cmpk_eq_i32 s74, 0xa8
	s_cselect_b32 s63, s5, s31
	s_cselect_b32 s62, s4, s30
	s_cselect_b32 s41, s27, s73
	s_cselect_b32 s40, s26, s72
	v_lshl_add_u64 v[146:147], s[28:29], 0, v[138:139]
	s_add_i32 m0, s15, 0xc000
	ds_read_b128 v[186:189], v152
	ds_read_b128 v[190:193], v152 offset:1024
	ds_read_b128 v[194:197], v152 offset:2048
	ds_read_b128 v[198:201], v152 offset:3072
	ds_read_b128 v[202:205], v152 offset:4096
	ds_read_b128 v[206:209], v152 offset:5120
	ds_read_b128 v[210:213], v152 offset:6144
	ds_read_b128 v[214:217], v152 offset:7168
	global_load_lds_dwordx4 v[146:147], off
	v_lshl_add_u64 v[146:147], s[28:29], 0, v[140:141]
	s_add_i32 m0, s15, 0xe000
	s_nop 0
	global_load_lds_dwordx4 v[146:147], off
	s_waitcnt vmcnt(8)
	s_waitcnt lgkmcnt(0)
	s_barrier
	s_setprio 1
	s_waitcnt lgkmcnt(0)
	v_mfma_f32_16x16x32_bf16 v[126:129], v[154:157], v[186:189], v[126:129]
	v_mfma_f32_16x16x32_bf16 v[122:125], v[162:165], v[186:189], v[122:125]
	v_mfma_f32_16x16x32_bf16 v[118:121], v[154:157], v[194:197], v[118:121]
	v_mfma_f32_16x16x32_bf16 v[110:113], v[162:165], v[194:197], v[110:113]
	v_mfma_f32_16x16x32_bf16 v[102:105], v[154:157], v[202:205], v[102:105]
	v_mfma_f32_16x16x32_bf16 v[94:97], v[162:165], v[202:205], v[94:97]
	v_mfma_f32_16x16x32_bf16 v[82:85], v[154:157], v[210:213], v[82:85]
	v_mfma_f32_16x16x32_bf16 v[74:77], v[162:165], v[210:213], v[74:77]
	v_mfma_f32_16x16x32_bf16 v[126:129], v[158:161], v[190:193], v[126:129]
	v_mfma_f32_16x16x32_bf16 v[122:125], v[166:169], v[190:193], v[122:125]
	v_mfma_f32_16x16x32_bf16 v[118:121], v[158:161], v[198:201], v[118:121]
	v_mfma_f32_16x16x32_bf16 v[110:113], v[166:169], v[198:201], v[110:113]
	v_mfma_f32_16x16x32_bf16 v[102:105], v[158:161], v[206:209], v[102:105]
	v_mfma_f32_16x16x32_bf16 v[94:97], v[166:169], v[206:209], v[94:97]
	v_mfma_f32_16x16x32_bf16 v[82:85], v[158:161], v[214:217], v[82:85]
	v_mfma_f32_16x16x32_bf16 v[74:77], v[166:169], v[214:217], v[74:77]
	v_mfma_f32_16x16x32_bf16 v[114:117], v[170:173], v[186:189], v[114:117]
	v_mfma_f32_16x16x32_bf16 v[106:109], v[178:181], v[186:189], v[106:109]
	v_mfma_f32_16x16x32_bf16 v[98:101], v[170:173], v[194:197], v[98:101]
	v_mfma_f32_16x16x32_bf16 v[90:93], v[178:181], v[194:197], v[90:93]
	v_mfma_f32_16x16x32_bf16 v[86:89], v[170:173], v[202:205], v[86:89]
	v_mfma_f32_16x16x32_bf16 v[78:81], v[178:181], v[202:205], v[78:81]
	v_mfma_f32_16x16x32_bf16 v[70:73], v[170:173], v[210:213], v[70:73]
	v_mfma_f32_16x16x32_bf16 v[66:69], v[178:181], v[210:213], v[66:69]
	v_mfma_f32_16x16x32_bf16 v[114:117], v[174:177], v[190:193], v[114:117]
	v_mfma_f32_16x16x32_bf16 v[106:109], v[182:185], v[190:193], v[106:109]
	v_mfma_f32_16x16x32_bf16 v[98:101], v[174:177], v[198:201], v[98:101]
	v_mfma_f32_16x16x32_bf16 v[90:93], v[182:185], v[198:201], v[90:93]
	v_mfma_f32_16x16x32_bf16 v[86:89], v[174:177], v[206:209], v[86:89]
	v_mfma_f32_16x16x32_bf16 v[78:81], v[182:185], v[206:209], v[78:81]
	v_mfma_f32_16x16x32_bf16 v[70:73], v[174:177], v[214:217], v[70:73]
	v_mfma_f32_16x16x32_bf16 v[66:69], v[182:185], v[214:217], v[66:69]
	s_setprio 0
	s_barrier
	s_add_i32 s28, s50, s3
	v_lshl_add_u64 v[146:147], s[40:41], 0, v[132:133]
	s_mov_b32 m0, s28
	ds_read_b128 v[186:189], v152 offset:16384
	ds_read_b128 v[190:193], v152 offset:17408
	ds_read_b128 v[194:197], v152 offset:18432
	ds_read_b128 v[198:201], v152 offset:19456
	ds_read_b128 v[202:205], v152 offset:20480
	ds_read_b128 v[206:209], v152 offset:21504
	ds_read_b128 v[210:213], v152 offset:22528
	ds_read_b128 v[214:217], v152 offset:23552
	global_load_lds_dwordx4 v[146:147], off
	s_add_i32 m0, s28, 0x2000
	s_add_u32 s28, s40, 0x2b0000
	v_lshl_add_u64 v[218:219], s[40:41], 0, v[136:137]
	s_addc_u32 s29, s41, 0
	s_add_i32 s75, s51, s3
	global_load_lds_dwordx4 v[218:219], off
	v_lshl_add_u64 v[220:221], s[28:29], 0, v[132:133]
	s_mov_b32 m0, s75
	v_lshl_add_u64 v[222:223], s[62:63], 0, v[134:135]
	global_load_lds_dwordx4 v[220:221], off
	v_lshl_add_u64 v[220:221], s[28:29], 0, v[136:137]
	s_add_i32 m0, s75, 0x2000
	s_nop 0
	global_load_lds_dwordx4 v[220:221], off
	v_lshl_add_u64 v[220:221], s[62:63], 0, v[130:131]
	s_mov_b32 m0, s15
	s_nop 0
	global_load_lds_dwordx4 v[220:221], off
	s_mov_b32 m0, s36
	s_nop 0
	global_load_lds_dwordx4 v[222:223], off
	s_waitcnt vmcnt(8)
	s_waitcnt lgkmcnt(0)
	s_barrier
	s_setprio 1
	s_waitcnt lgkmcnt(0)
	v_mfma_f32_16x16x32_bf16 v[62:65], v[154:157], v[186:189], v[62:65]
	v_mfma_f32_16x16x32_bf16 v[58:61], v[162:165], v[186:189], v[58:61]
	v_mfma_f32_16x16x32_bf16 v[54:57], v[154:157], v[194:197], v[54:57]
	v_mfma_f32_16x16x32_bf16 v[46:49], v[162:165], v[194:197], v[46:49]
	v_mfma_f32_16x16x32_bf16 v[38:41], v[154:157], v[202:205], v[38:41]
	v_mfma_f32_16x16x32_bf16 v[30:33], v[162:165], v[202:205], v[30:33]
	v_mfma_f32_16x16x32_bf16 v[22:25], v[154:157], v[210:213], v[22:25]
	v_mfma_f32_16x16x32_bf16 v[14:17], v[162:165], v[210:213], v[14:17]
	v_mfma_f32_16x16x32_bf16 v[62:65], v[158:161], v[190:193], v[62:65]
	v_mfma_f32_16x16x32_bf16 v[58:61], v[166:169], v[190:193], v[58:61]
	v_mfma_f32_16x16x32_bf16 v[54:57], v[158:161], v[198:201], v[54:57]
	v_mfma_f32_16x16x32_bf16 v[46:49], v[166:169], v[198:201], v[46:49]
	v_mfma_f32_16x16x32_bf16 v[38:41], v[158:161], v[206:209], v[38:41]
	v_mfma_f32_16x16x32_bf16 v[30:33], v[166:169], v[206:209], v[30:33]
	v_mfma_f32_16x16x32_bf16 v[22:25], v[158:161], v[214:217], v[22:25]
	v_mfma_f32_16x16x32_bf16 v[14:17], v[166:169], v[214:217], v[14:17]
	v_mfma_f32_16x16x32_bf16 v[50:53], v[170:173], v[186:189], v[50:53]
	v_mfma_f32_16x16x32_bf16 v[42:45], v[178:181], v[186:189], v[42:45]
	v_mfma_f32_16x16x32_bf16 v[34:37], v[170:173], v[194:197], v[34:37]
	v_mfma_f32_16x16x32_bf16 v[26:29], v[178:181], v[194:197], v[26:29]
	v_mfma_f32_16x16x32_bf16 v[18:21], v[170:173], v[202:205], v[18:21]
	v_mfma_f32_16x16x32_bf16 v[10:13], v[178:181], v[202:205], v[10:13]
	v_mfma_f32_16x16x32_bf16 v[6:9], v[170:173], v[210:213], v[6:9]
	v_mfma_f32_16x16x32_bf16 v[2:5], v[178:181], v[210:213], v[2:5]
	v_mfma_f32_16x16x32_bf16 v[50:53], v[174:177], v[190:193], v[50:53]
	v_mfma_f32_16x16x32_bf16 v[42:45], v[182:185], v[190:193], v[42:45]
	v_mfma_f32_16x16x32_bf16 v[34:37], v[174:177], v[198:201], v[34:37]
	v_mfma_f32_16x16x32_bf16 v[26:29], v[182:185], v[198:201], v[26:29]
	v_mfma_f32_16x16x32_bf16 v[18:21], v[174:177], v[206:209], v[18:21]
	v_mfma_f32_16x16x32_bf16 v[10:13], v[182:185], v[206:209], v[10:13]
	v_mfma_f32_16x16x32_bf16 v[6:9], v[174:177], v[214:217], v[6:9]
	v_mfma_f32_16x16x32_bf16 v[2:5], v[182:185], v[214:217], v[2:5]
	s_setprio 0
	s_barrier
	s_add_i32 s75, 0, 0x18000
	v_add_u32_e32 v153, s75, v148
	s_add_i32 s76, 0, 0x1c000
	ds_read_b128 v[154:157], v153
	ds_read_b128 v[158:161], v153 offset:1024
	ds_read_b128 v[162:165], v153 offset:2048
	ds_read_b128 v[166:169], v153 offset:3072
	v_add_u32_e32 v153, s76, v148
	ds_read_b128 v[170:173], v153
	ds_read_b128 v[174:177], v153 offset:1024
	ds_read_b128 v[178:181], v153 offset:2048
	ds_read_b128 v[182:185], v153 offset:3072
	s_add_u32 s28, s62, 0x2b0000
	s_addc_u32 s29, s63, 0
	s_mov_b32 m0, s37
	v_lshl_add_u64 v[224:225], s[28:29], 0, v[130:131]
	ds_read_b128 v[186:189], v152 offset:32768
	ds_read_b128 v[190:193], v152 offset:33792
	ds_read_b128 v[194:197], v152 offset:34816
	ds_read_b128 v[198:201], v152 offset:35840
	ds_read_b128 v[202:205], v152 offset:36864
	ds_read_b128 v[206:209], v152 offset:37888
	ds_read_b128 v[210:213], v152 offset:38912
	ds_read_b128 v[214:217], v152 offset:39936
	global_load_lds_dwordx4 v[224:225], off
	v_lshl_add_u64 v[224:225], s[28:29], 0, v[134:135]
	s_mov_b32 m0, s42
	s_nop 0
	global_load_lds_dwordx4 v[224:225], off
	s_waitcnt vmcnt(8)
	s_waitcnt lgkmcnt(0)
	s_barrier
	s_setprio 1
	s_waitcnt lgkmcnt(0)
	v_mfma_f32_16x16x32_bf16 v[126:129], v[154:157], v[186:189], v[126:129]
	v_mfma_f32_16x16x32_bf16 v[122:125], v[162:165], v[186:189], v[122:125]
	v_mfma_f32_16x16x32_bf16 v[118:121], v[154:157], v[194:197], v[118:121]
	v_mfma_f32_16x16x32_bf16 v[110:113], v[162:165], v[194:197], v[110:113]
	v_mfma_f32_16x16x32_bf16 v[102:105], v[154:157], v[202:205], v[102:105]
	v_mfma_f32_16x16x32_bf16 v[94:97], v[162:165], v[202:205], v[94:97]
	v_mfma_f32_16x16x32_bf16 v[82:85], v[154:157], v[210:213], v[82:85]
	v_mfma_f32_16x16x32_bf16 v[74:77], v[162:165], v[210:213], v[74:77]
	v_mfma_f32_16x16x32_bf16 v[126:129], v[158:161], v[190:193], v[126:129]
	v_mfma_f32_16x16x32_bf16 v[122:125], v[166:169], v[190:193], v[122:125]
	v_mfma_f32_16x16x32_bf16 v[118:121], v[158:161], v[198:201], v[118:121]
	v_mfma_f32_16x16x32_bf16 v[110:113], v[166:169], v[198:201], v[110:113]
	v_mfma_f32_16x16x32_bf16 v[102:105], v[158:161], v[206:209], v[102:105]
	v_mfma_f32_16x16x32_bf16 v[94:97], v[166:169], v[206:209], v[94:97]
	v_mfma_f32_16x16x32_bf16 v[82:85], v[158:161], v[214:217], v[82:85]
	v_mfma_f32_16x16x32_bf16 v[74:77], v[166:169], v[214:217], v[74:77]
	v_mfma_f32_16x16x32_bf16 v[114:117], v[170:173], v[186:189], v[114:117]
	v_mfma_f32_16x16x32_bf16 v[106:109], v[178:181], v[186:189], v[106:109]
	v_mfma_f32_16x16x32_bf16 v[98:101], v[170:173], v[194:197], v[98:101]
	v_mfma_f32_16x16x32_bf16 v[90:93], v[178:181], v[194:197], v[90:93]
	v_mfma_f32_16x16x32_bf16 v[86:89], v[170:173], v[202:205], v[86:89]
	v_mfma_f32_16x16x32_bf16 v[78:81], v[178:181], v[202:205], v[78:81]
	v_mfma_f32_16x16x32_bf16 v[70:73], v[170:173], v[210:213], v[70:73]
	v_mfma_f32_16x16x32_bf16 v[66:69], v[178:181], v[210:213], v[66:69]
	v_mfma_f32_16x16x32_bf16 v[114:117], v[174:177], v[190:193], v[114:117]
	v_mfma_f32_16x16x32_bf16 v[106:109], v[182:185], v[190:193], v[106:109]
	v_mfma_f32_16x16x32_bf16 v[98:101], v[174:177], v[198:201], v[98:101]
	v_mfma_f32_16x16x32_bf16 v[90:93], v[182:185], v[198:201], v[90:93]
	v_mfma_f32_16x16x32_bf16 v[86:89], v[174:177], v[206:209], v[86:89]
	v_mfma_f32_16x16x32_bf16 v[78:81], v[182:185], v[206:209], v[78:81]
	v_mfma_f32_16x16x32_bf16 v[70:73], v[174:177], v[214:217], v[70:73]
	v_mfma_f32_16x16x32_bf16 v[66:69], v[182:185], v[214:217], v[66:69]
	s_setprio 0
	s_barrier
	s_add_i32 s28, s75, s3
	v_lshl_add_u64 v[146:147], v[146:147], 0, s[22:23]
	s_mov_b32 m0, s28
	ds_read_b128 v[186:189], v152 offset:49152
	ds_read_b128 v[190:193], v152 offset:50176
	ds_read_b128 v[194:197], v152 offset:51200
	ds_read_b128 v[198:201], v152 offset:52224
	ds_read_b128 v[202:205], v152 offset:53248
	ds_read_b128 v[206:209], v152 offset:54272
	ds_read_b128 v[210:213], v152 offset:55296
	ds_read_b128 v[214:217], v152 offset:56320
	global_load_lds_dwordx4 v[146:147], off
	s_add_i32 m0, s28, 0x2000
	s_add_u32 s28, s40, 0x2b0080
	v_lshl_add_u64 v[146:147], v[218:219], 0, s[22:23]
	s_addc_u32 s29, s41, 0
	s_add_i32 s40, s76, s3
	global_load_lds_dwordx4 v[146:147], off
	v_lshl_add_u64 v[146:147], s[28:29], 0, v[132:133]
	s_mov_b32 m0, s40
	s_nop 0
	global_load_lds_dwordx4 v[146:147], off
	v_lshl_add_u64 v[146:147], s[28:29], 0, v[136:137]
	s_add_i32 m0, s40, 0x2000
	s_nop 0
	global_load_lds_dwordx4 v[146:147], off
	v_lshl_add_u64 v[146:147], v[220:221], 0, s[22:23]
	s_mov_b32 m0, s44
	s_nop 0
	global_load_lds_dwordx4 v[146:147], off
	v_lshl_add_u64 v[146:147], v[222:223], 0, s[22:23]
	s_mov_b32 m0, s45
	s_nop 0
	global_load_lds_dwordx4 v[146:147], off
	s_waitcnt vmcnt(8)
	s_waitcnt lgkmcnt(0)
	s_barrier
	s_setprio 1
	s_waitcnt lgkmcnt(0)
	v_mfma_f32_16x16x32_bf16 v[62:65], v[154:157], v[186:189], v[62:65]
	v_mfma_f32_16x16x32_bf16 v[58:61], v[162:165], v[186:189], v[58:61]
	v_mfma_f32_16x16x32_bf16 v[54:57], v[154:157], v[194:197], v[54:57]
	v_mfma_f32_16x16x32_bf16 v[46:49], v[162:165], v[194:197], v[46:49]
	v_mfma_f32_16x16x32_bf16 v[38:41], v[154:157], v[202:205], v[38:41]
	v_mfma_f32_16x16x32_bf16 v[30:33], v[162:165], v[202:205], v[30:33]
	v_mfma_f32_16x16x32_bf16 v[22:25], v[154:157], v[210:213], v[22:25]
	v_mfma_f32_16x16x32_bf16 v[14:17], v[162:165], v[210:213], v[14:17]
	v_mfma_f32_16x16x32_bf16 v[62:65], v[158:161], v[190:193], v[62:65]
	v_mfma_f32_16x16x32_bf16 v[58:61], v[166:169], v[190:193], v[58:61]
	v_mfma_f32_16x16x32_bf16 v[54:57], v[158:161], v[198:201], v[54:57]
	v_mfma_f32_16x16x32_bf16 v[46:49], v[166:169], v[198:201], v[46:49]
	v_mfma_f32_16x16x32_bf16 v[38:41], v[158:161], v[206:209], v[38:41]
	v_mfma_f32_16x16x32_bf16 v[30:33], v[166:169], v[206:209], v[30:33]
	v_mfma_f32_16x16x32_bf16 v[22:25], v[158:161], v[214:217], v[22:25]
	v_mfma_f32_16x16x32_bf16 v[14:17], v[166:169], v[214:217], v[14:17]
	v_mfma_f32_16x16x32_bf16 v[50:53], v[170:173], v[186:189], v[50:53]
	v_mfma_f32_16x16x32_bf16 v[42:45], v[178:181], v[186:189], v[42:45]
	v_mfma_f32_16x16x32_bf16 v[34:37], v[170:173], v[194:197], v[34:37]
	v_mfma_f32_16x16x32_bf16 v[26:29], v[178:181], v[194:197], v[26:29]
	v_mfma_f32_16x16x32_bf16 v[18:21], v[170:173], v[202:205], v[18:21]
	v_mfma_f32_16x16x32_bf16 v[10:13], v[178:181], v[202:205], v[10:13]
	v_mfma_f32_16x16x32_bf16 v[6:9], v[170:173], v[210:213], v[6:9]
	v_mfma_f32_16x16x32_bf16 v[2:5], v[178:181], v[210:213], v[2:5]
	v_mfma_f32_16x16x32_bf16 v[50:53], v[174:177], v[190:193], v[50:53]
	v_mfma_f32_16x16x32_bf16 v[42:45], v[182:185], v[190:193], v[42:45]
	v_mfma_f32_16x16x32_bf16 v[34:37], v[174:177], v[198:201], v[34:37]
	v_mfma_f32_16x16x32_bf16 v[26:29], v[182:185], v[198:201], v[26:29]
	v_mfma_f32_16x16x32_bf16 v[18:21], v[174:177], v[206:209], v[18:21]
	v_mfma_f32_16x16x32_bf16 v[10:13], v[182:185], v[206:209], v[10:13]
	v_mfma_f32_16x16x32_bf16 v[6:9], v[174:177], v[214:217], v[6:9]
	v_mfma_f32_16x16x32_bf16 v[2:5], v[182:185], v[214:217], v[2:5]
	s_setprio 0
	s_barrier
	s_add_i32 s74, s74, 2
	s_add_u32 s72, s72, 0x100
	s_addc_u32 s73, s73, 0
	s_cmpk_gt_u32 s74, 0xa9
	s_mov_b64 s[28:29], s[30:31]
	s_cbranch_scc0 .LBB0_260
	s_and_b64 vcc, exec, s[24:25]
	s_cbranch_vccz .LBB0_263
	s_barrier

.LBB0_387:
	ds_read_b128 v[152:155], v148
	ds_read_b128 v[156:159], v148 offset:1024
	ds_read_b128 v[160:163], v148 offset:2048
	ds_read_b128 v[164:167], v148 offset:3072
	ds_read_b128 v[168:171], v149
	ds_read_b128 v[172:175], v149 offset:1024
	ds_read_b128 v[176:179], v149 offset:2048
	ds_read_b128 v[180:183], v149 offset:3072
	s_add_u32 s40, s30, 0xfff00080
	s_addc_u32 s41, s31, -1
	s_cmp_eq_u32 s71, 60
	s_cselect_b32 s69, s23, s41
	s_cselect_b32 s68, s63, s40
	s_cselect_b32 s41, s13, s70
	s_cselect_b32 s40, s66, s67
	v_lshl_add_u64 v[144:145], s[30:31], 0, v[134:135]
	s_add_i32 m0, s29, 0xc000
	ds_read_b128 v[184:187], v150
	ds_read_b128 v[188:191], v150 offset:1024
	ds_read_b128 v[192:195], v150 offset:2048
	ds_read_b128 v[196:199], v150 offset:3072
	ds_read_b128 v[200:203], v150 offset:4096
	ds_read_b128 v[204:207], v150 offset:5120
	ds_read_b128 v[208:211], v150 offset:6144
	ds_read_b128 v[212:215], v150 offset:7168
	global_load_lds_dwordx4 v[144:145], off
	v_lshl_add_u64 v[144:145], s[30:31], 0, v[136:137]
	s_add_i32 m0, s29, 0xe000
	s_nop 0
	global_load_lds_dwordx4 v[144:145], off
	s_waitcnt vmcnt(8)
	s_waitcnt lgkmcnt(0)
	s_barrier
	s_setprio 1
	s_waitcnt lgkmcnt(0)
	v_mfma_f32_16x16x32_bf16 v[126:129], v[152:155], v[184:187], v[126:129]
	v_mfma_f32_16x16x32_bf16 v[122:125], v[160:163], v[184:187], v[122:125]
	v_mfma_f32_16x16x32_bf16 v[114:117], v[152:155], v[192:195], v[114:117]
	v_mfma_f32_16x16x32_bf16 v[106:109], v[160:163], v[192:195], v[106:109]
	v_mfma_f32_16x16x32_bf16 v[98:101], v[152:155], v[200:203], v[98:101]
	v_mfma_f32_16x16x32_bf16 v[90:93], v[160:163], v[200:203], v[90:93]
	v_mfma_f32_16x16x32_bf16 v[82:85], v[152:155], v[208:211], v[82:85]
	v_mfma_f32_16x16x32_bf16 v[74:77], v[160:163], v[208:211], v[74:77]
	v_mfma_f32_16x16x32_bf16 v[126:129], v[156:159], v[188:191], v[126:129]
	v_mfma_f32_16x16x32_bf16 v[122:125], v[164:167], v[188:191], v[122:125]
	v_mfma_f32_16x16x32_bf16 v[114:117], v[156:159], v[196:199], v[114:117]
	v_mfma_f32_16x16x32_bf16 v[106:109], v[164:167], v[196:199], v[106:109]
	v_mfma_f32_16x16x32_bf16 v[98:101], v[156:159], v[204:207], v[98:101]
	v_mfma_f32_16x16x32_bf16 v[90:93], v[164:167], v[204:207], v[90:93]
	v_mfma_f32_16x16x32_bf16 v[82:85], v[156:159], v[212:215], v[82:85]
	v_mfma_f32_16x16x32_bf16 v[74:77], v[164:167], v[212:215], v[74:77]
	v_mfma_f32_16x16x32_bf16 v[118:121], v[168:171], v[184:187], v[118:121]
	v_mfma_f32_16x16x32_bf16 v[110:113], v[176:179], v[184:187], v[110:113]
	v_mfma_f32_16x16x32_bf16 v[102:105], v[168:171], v[192:195], v[102:105]
	v_mfma_f32_16x16x32_bf16 v[94:97], v[176:179], v[192:195], v[94:97]
	v_mfma_f32_16x16x32_bf16 v[86:89], v[168:171], v[200:203], v[86:89]
	v_mfma_f32_16x16x32_bf16 v[78:81], v[176:179], v[200:203], v[78:81]
	v_mfma_f32_16x16x32_bf16 v[70:73], v[168:171], v[208:211], v[70:73]
	v_mfma_f32_16x16x32_bf16 v[66:69], v[176:179], v[208:211], v[66:69]
	v_mfma_f32_16x16x32_bf16 v[118:121], v[172:175], v[188:191], v[118:121]
	v_mfma_f32_16x16x32_bf16 v[110:113], v[180:183], v[188:191], v[110:113]
	v_mfma_f32_16x16x32_bf16 v[102:105], v[172:175], v[196:199], v[102:105]
	v_mfma_f32_16x16x32_bf16 v[94:97], v[180:183], v[196:199], v[94:97]
	v_mfma_f32_16x16x32_bf16 v[86:89], v[172:175], v[204:207], v[86:89]
	v_mfma_f32_16x16x32_bf16 v[78:81], v[180:183], v[204:207], v[78:81]
	v_mfma_f32_16x16x32_bf16 v[70:73], v[172:175], v[212:215], v[70:73]
	v_mfma_f32_16x16x32_bf16 v[66:69], v[180:183], v[212:215], v[66:69]
	s_setprio 0
	s_barrier
	s_add_i32 s72, s50, s36
	v_lshl_add_u64 v[144:145], s[40:41], 0, v[132:133]
	s_mov_b32 m0, s72
	ds_read_b128 v[184:187], v150 offset:16384
	ds_read_b128 v[188:191], v150 offset:17408
	ds_read_b128 v[192:195], v150 offset:18432
	ds_read_b128 v[196:199], v150 offset:19456
	ds_read_b128 v[200:203], v150 offset:20480
	ds_read_b128 v[204:207], v150 offset:21504
	ds_read_b128 v[208:211], v150 offset:22528
	ds_read_b128 v[212:215], v150 offset:23552
	global_load_lds_dwordx4 v[144:145], off
	s_add_i32 m0, s72, 0x2000
	s_add_u32 s72, s40, 0x100000
	v_lshl_add_u64 v[216:217], s[40:41], 0, v[130:131]
	s_addc_u32 s73, s41, 0
	s_add_i32 s74, s51, s36
	global_load_lds_dwordx4 v[216:217], off
	v_lshl_add_u64 v[218:219], s[72:73], 0, v[132:133]
	s_mov_b32 m0, s74
	v_lshl_add_u64 v[220:221], s[68:69], 0, v[130:131]
	global_load_lds_dwordx4 v[218:219], off
	v_lshl_add_u64 v[218:219], s[72:73], 0, v[130:131]
	s_add_i32 m0, s74, 0x2000
	s_nop 0
	global_load_lds_dwordx4 v[218:219], off
	v_lshl_add_u64 v[218:219], s[68:69], 0, v[132:133]
	s_mov_b32 m0, s29
	s_nop 0
	global_load_lds_dwordx4 v[218:219], off
	s_mov_b32 m0, s43
	s_nop 0
	global_load_lds_dwordx4 v[220:221], off
	s_waitcnt vmcnt(8)
	s_waitcnt lgkmcnt(0)
	s_barrier
	s_setprio 1
	s_waitcnt lgkmcnt(0)
	v_mfma_f32_16x16x32_bf16 v[62:65], v[152:155], v[184:187], v[62:65]
	v_mfma_f32_16x16x32_bf16 v[58:61], v[160:163], v[184:187], v[58:61]
	v_mfma_f32_16x16x32_bf16 v[50:53], v[152:155], v[192:195], v[50:53]
	v_mfma_f32_16x16x32_bf16 v[42:45], v[160:163], v[192:195], v[42:45]
	v_mfma_f32_16x16x32_bf16 v[34:37], v[152:155], v[200:203], v[34:37]
	v_mfma_f32_16x16x32_bf16 v[26:29], v[160:163], v[200:203], v[26:29]
	v_mfma_f32_16x16x32_bf16 v[18:21], v[152:155], v[208:211], v[18:21]
	v_mfma_f32_16x16x32_bf16 v[10:13], v[160:163], v[208:211], v[10:13]
	v_mfma_f32_16x16x32_bf16 v[62:65], v[156:159], v[188:191], v[62:65]
	v_mfma_f32_16x16x32_bf16 v[58:61], v[164:167], v[188:191], v[58:61]
	v_mfma_f32_16x16x32_bf16 v[50:53], v[156:159], v[196:199], v[50:53]
	v_mfma_f32_16x16x32_bf16 v[42:45], v[164:167], v[196:199], v[42:45]
	v_mfma_f32_16x16x32_bf16 v[34:37], v[156:159], v[204:207], v[34:37]
	v_mfma_f32_16x16x32_bf16 v[26:29], v[164:167], v[204:207], v[26:29]
	v_mfma_f32_16x16x32_bf16 v[18:21], v[156:159], v[212:215], v[18:21]
	v_mfma_f32_16x16x32_bf16 v[10:13], v[164:167], v[212:215], v[10:13]
	v_mfma_f32_16x16x32_bf16 v[54:57], v[168:171], v[184:187], v[54:57]
	v_mfma_f32_16x16x32_bf16 v[46:49], v[176:179], v[184:187], v[46:49]
	v_mfma_f32_16x16x32_bf16 v[38:41], v[168:171], v[192:195], v[38:41]
	v_mfma_f32_16x16x32_bf16 v[30:33], v[176:179], v[192:195], v[30:33]
	v_mfma_f32_16x16x32_bf16 v[22:25], v[168:171], v[200:203], v[22:25]
	v_mfma_f32_16x16x32_bf16 v[14:17], v[176:179], v[200:203], v[14:17]
	v_mfma_f32_16x16x32_bf16 v[6:9], v[168:171], v[208:211], v[6:9]
	v_mfma_f32_16x16x32_bf16 v[2:5], v[176:179], v[208:211], v[2:5]
	v_mfma_f32_16x16x32_bf16 v[54:57], v[172:175], v[188:191], v[54:57]
	v_mfma_f32_16x16x32_bf16 v[46:49], v[180:183], v[188:191], v[46:49]
	v_mfma_f32_16x16x32_bf16 v[38:41], v[172:175], v[196:199], v[38:41]
	v_mfma_f32_16x16x32_bf16 v[30:33], v[180:183], v[196:199], v[30:33]
	v_mfma_f32_16x16x32_bf16 v[22:25], v[172:175], v[204:207], v[22:25]
	v_mfma_f32_16x16x32_bf16 v[14:17], v[180:183], v[204:207], v[14:17]
	v_mfma_f32_16x16x32_bf16 v[6:9], v[172:175], v[212:215], v[6:9]
	v_mfma_f32_16x16x32_bf16 v[2:5], v[180:183], v[212:215], v[2:5]
	s_setprio 0
	s_barrier
	s_add_i32 s72, 0, 0x18000
	v_add_u32_e32 v142, s72, v146
	s_add_i32 s73, 0, 0x1c000
	ds_read_b128 v[152:155], v142
	ds_read_b128 v[156:159], v142 offset:1024
	ds_read_b128 v[160:163], v142 offset:2048
	ds_read_b128 v[164:167], v142 offset:3072
	v_add_u32_e32 v142, s73, v146
	ds_read_b128 v[168:171], v142
	ds_read_b128 v[172:175], v142 offset:1024
	ds_read_b128 v[176:179], v142 offset:2048
	ds_read_b128 v[180:183], v142 offset:3072
	s_add_u32 s68, s68, 0x100000
	s_addc_u32 s69, s69, 0
	s_mov_b32 m0, s44
	v_lshl_add_u64 v[222:223], s[68:69], 0, v[132:133]
	ds_read_b128 v[184:187], v150 offset:32768
	ds_read_b128 v[188:191], v150 offset:33792
	ds_read_b128 v[192:195], v150 offset:34816
	ds_read_b128 v[196:199], v150 offset:35840
	ds_read_b128 v[200:203], v150 offset:36864
	ds_read_b128 v[204:207], v150 offset:37888
	ds_read_b128 v[208:211], v150 offset:38912
	ds_read_b128 v[212:215], v150 offset:39936
	global_load_lds_dwordx4 v[222:223], off
	v_lshl_add_u64 v[222:223], s[68:69], 0, v[130:131]
	s_mov_b32 m0, s45
	s_nop 0
	global_load_lds_dwordx4 v[222:223], off
	s_waitcnt vmcnt(8)
	s_waitcnt lgkmcnt(0)
	s_barrier
	s_setprio 1
	s_waitcnt lgkmcnt(0)
	v_mfma_f32_16x16x32_bf16 v[126:129], v[152:155], v[184:187], v[126:129]
	v_mfma_f32_16x16x32_bf16 v[122:125], v[160:163], v[184:187], v[122:125]
	v_mfma_f32_16x16x32_bf16 v[114:117], v[152:155], v[192:195], v[114:117]
	v_mfma_f32_16x16x32_bf16 v[106:109], v[160:163], v[192:195], v[106:109]
	v_mfma_f32_16x16x32_bf16 v[98:101], v[152:155], v[200:203], v[98:101]
	v_mfma_f32_16x16x32_bf16 v[90:93], v[160:163], v[200:203], v[90:93]
	v_mfma_f32_16x16x32_bf16 v[82:85], v[152:155], v[208:211], v[82:85]
	v_mfma_f32_16x16x32_bf16 v[74:77], v[160:163], v[208:211], v[74:77]
	v_mfma_f32_16x16x32_bf16 v[126:129], v[156:159], v[188:191], v[126:129]
	v_mfma_f32_16x16x32_bf16 v[122:125], v[164:167], v[188:191], v[122:125]
	v_mfma_f32_16x16x32_bf16 v[114:117], v[156:159], v[196:199], v[114:117]
	v_mfma_f32_16x16x32_bf16 v[106:109], v[164:167], v[196:199], v[106:109]
	v_mfma_f32_16x16x32_bf16 v[98:101], v[156:159], v[204:207], v[98:101]
	v_mfma_f32_16x16x32_bf16 v[90:93], v[164:167], v[204:207], v[90:93]
	v_mfma_f32_16x16x32_bf16 v[82:85], v[156:159], v[212:215], v[82:85]
	v_mfma_f32_16x16x32_bf16 v[74:77], v[164:167], v[212:215], v[74:77]
	v_mfma_f32_16x16x32_bf16 v[118:121], v[168:171], v[184:187], v[118:121]
	v_mfma_f32_16x16x32_bf16 v[110:113], v[176:179], v[184:187], v[110:113]
	v_mfma_f32_16x16x32_bf16 v[102:105], v[168:171], v[192:195], v[102:105]
	v_mfma_f32_16x16x32_bf16 v[94:97], v[176:179], v[192:195], v[94:97]
	v_mfma_f32_16x16x32_bf16 v[86:89], v[168:171], v[200:203], v[86:89]
	v_mfma_f32_16x16x32_bf16 v[78:81], v[176:179], v[200:203], v[78:81]
	v_mfma_f32_16x16x32_bf16 v[70:73], v[168:171], v[208:211], v[70:73]
	v_mfma_f32_16x16x32_bf16 v[66:69], v[176:179], v[208:211], v[66:69]
	v_mfma_f32_16x16x32_bf16 v[118:121], v[172:175], v[188:191], v[118:121]
	v_mfma_f32_16x16x32_bf16 v[110:113], v[180:183], v[188:191], v[110:113]
	v_mfma_f32_16x16x32_bf16 v[102:105], v[172:175], v[196:199], v[102:105]
	v_mfma_f32_16x16x32_bf16 v[94:97], v[180:183], v[196:199], v[94:97]
	v_mfma_f32_16x16x32_bf16 v[86:89], v[172:175], v[204:207], v[86:89]
	v_mfma_f32_16x16x32_bf16 v[78:81], v[180:183], v[204:207], v[78:81]
	v_mfma_f32_16x16x32_bf16 v[70:73], v[172:175], v[212:215], v[70:73]
	v_mfma_f32_16x16x32_bf16 v[66:69], v[180:183], v[212:215], v[66:69]
	s_setprio 0
	s_barrier
	s_add_i32 s68, s72, s36
	v_lshl_add_u64 v[144:145], v[144:145], 0, s[8:9]
	s_mov_b32 m0, s68
	ds_read_b128 v[184:187], v150 offset:49152
	ds_read_b128 v[188:191], v150 offset:50176
	ds_read_b128 v[192:195], v150 offset:51200
	ds_read_b128 v[196:199], v150 offset:52224
	ds_read_b128 v[200:203], v150 offset:53248
	ds_read_b128 v[204:207], v150 offset:54272
	ds_read_b128 v[208:211], v150 offset:55296
	ds_read_b128 v[212:215], v150 offset:56320
	global_load_lds_dwordx4 v[144:145], off
	s_add_i32 m0, s68, 0x2000
	s_add_u32 s40, s40, 0x100080
	v_lshl_add_u64 v[144:145], v[216:217], 0, s[8:9]
	s_addc_u32 s41, s41, 0
	s_add_i32 s68, s73, s36
	global_load_lds_dwordx4 v[144:145], off
	v_lshl_add_u64 v[144:145], s[40:41], 0, v[132:133]
	s_mov_b32 m0, s68
	s_nop 0
	global_load_lds_dwordx4 v[144:145], off
	v_lshl_add_u64 v[144:145], s[40:41], 0, v[130:131]
	s_add_i32 m0, s68, 0x2000
	s_nop 0
	global_load_lds_dwordx4 v[144:145], off
	v_lshl_add_u64 v[144:145], v[218:219], 0, s[8:9]
	s_mov_b32 m0, s47
	s_nop 0
	global_load_lds_dwordx4 v[144:145], off
	v_lshl_add_u64 v[144:145], v[220:221], 0, s[8:9]
	s_mov_b32 m0, s48
	s_nop 0
	global_load_lds_dwordx4 v[144:145], off
	s_waitcnt vmcnt(8)
	s_waitcnt lgkmcnt(0)
	s_barrier
	s_setprio 1
	s_waitcnt lgkmcnt(0)
	v_mfma_f32_16x16x32_bf16 v[62:65], v[152:155], v[184:187], v[62:65]
	v_mfma_f32_16x16x32_bf16 v[58:61], v[160:163], v[184:187], v[58:61]
	v_mfma_f32_16x16x32_bf16 v[50:53], v[152:155], v[192:195], v[50:53]
	v_mfma_f32_16x16x32_bf16 v[42:45], v[160:163], v[192:195], v[42:45]
	v_mfma_f32_16x16x32_bf16 v[34:37], v[152:155], v[200:203], v[34:37]
	v_mfma_f32_16x16x32_bf16 v[26:29], v[160:163], v[200:203], v[26:29]
	v_mfma_f32_16x16x32_bf16 v[18:21], v[152:155], v[208:211], v[18:21]
	v_mfma_f32_16x16x32_bf16 v[10:13], v[160:163], v[208:211], v[10:13]
	v_mfma_f32_16x16x32_bf16 v[62:65], v[156:159], v[188:191], v[62:65]
	v_mfma_f32_16x16x32_bf16 v[58:61], v[164:167], v[188:191], v[58:61]
	v_mfma_f32_16x16x32_bf16 v[50:53], v[156:159], v[196:199], v[50:53]
	v_mfma_f32_16x16x32_bf16 v[42:45], v[164:167], v[196:199], v[42:45]
	v_mfma_f32_16x16x32_bf16 v[34:37], v[156:159], v[204:207], v[34:37]
	v_mfma_f32_16x16x32_bf16 v[26:29], v[164:167], v[204:207], v[26:29]
	v_mfma_f32_16x16x32_bf16 v[18:21], v[156:159], v[212:215], v[18:21]
	v_mfma_f32_16x16x32_bf16 v[10:13], v[164:167], v[212:215], v[10:13]
	v_mfma_f32_16x16x32_bf16 v[54:57], v[168:171], v[184:187], v[54:57]
	v_mfma_f32_16x16x32_bf16 v[46:49], v[176:179], v[184:187], v[46:49]
	v_mfma_f32_16x16x32_bf16 v[38:41], v[168:171], v[192:195], v[38:41]
	v_mfma_f32_16x16x32_bf16 v[30:33], v[176:179], v[192:195], v[30:33]
	v_mfma_f32_16x16x32_bf16 v[22:25], v[168:171], v[200:203], v[22:25]
	v_mfma_f32_16x16x32_bf16 v[14:17], v[176:179], v[200:203], v[14:17]
	v_mfma_f32_16x16x32_bf16 v[6:9], v[168:171], v[208:211], v[6:9]
	v_mfma_f32_16x16x32_bf16 v[2:5], v[176:179], v[208:211], v[2:5]
	v_mfma_f32_16x16x32_bf16 v[54:57], v[172:175], v[188:191], v[54:57]
	v_mfma_f32_16x16x32_bf16 v[46:49], v[180:183], v[188:191], v[46:49]
	v_mfma_f32_16x16x32_bf16 v[38:41], v[172:175], v[196:199], v[38:41]
	v_mfma_f32_16x16x32_bf16 v[30:33], v[180:183], v[196:199], v[30:33]
	v_mfma_f32_16x16x32_bf16 v[22:25], v[172:175], v[204:207], v[22:25]
	v_mfma_f32_16x16x32_bf16 v[14:17], v[180:183], v[204:207], v[14:17]
	v_mfma_f32_16x16x32_bf16 v[6:9], v[172:175], v[212:215], v[6:9]
	v_mfma_f32_16x16x32_bf16 v[2:5], v[180:183], v[212:215], v[2:5]
	s_setprio 0
	s_barrier
	s_add_i32 s71, s71, 2
	s_add_u32 s30, s30, 0x100
	s_addc_u32 s31, s31, 0
	s_add_u32 s67, s67, 0x100
	s_addc_u32 s70, s70, 0
	s_cmp_gt_u32 s71, 61
	s_cbranch_scc0 .LBB0_387
	s_and_b64 vcc, exec, s[10:11]
	s_cbranch_vccz .LBB0_390
	s_barrier

.LBB0_1211:
	ds_read_b128 v[154:157], v150
	ds_read_b128 v[158:161], v150 offset:1024
	ds_read_b128 v[162:165], v150 offset:2048
	ds_read_b128 v[166:169], v150 offset:3072
	ds_read_b128 v[170:173], v151
	ds_read_b128 v[174:177], v151 offset:1024
	ds_read_b128 v[178:181], v151 offset:2048
	ds_read_b128 v[182:185], v151 offset:3072
	s_add_u32 s40, s36, 0xfff00080
	s_addc_u32 s41, s37, -1
	s_cmp_eq_u32 s64, 60
	s_cselect_b32 s43, s25, s41
	s_cselect_b32 s42, s60, s40
	s_cselect_b32 s41, s23, s63
	s_cselect_b32 s40, s61, s62
	v_lshl_add_u64 v[146:147], s[36:37], 0, v[138:139]
	s_add_i32 m0, s31, 0xc000
	ds_read_b128 v[186:189], v152
	ds_read_b128 v[190:193], v152 offset:1024
	ds_read_b128 v[194:197], v152 offset:2048
	ds_read_b128 v[198:201], v152 offset:3072
	ds_read_b128 v[202:205], v152 offset:4096
	ds_read_b128 v[206:209], v152 offset:5120
	ds_read_b128 v[210:213], v152 offset:6144
	ds_read_b128 v[214:217], v152 offset:7168
	global_load_lds_dwordx4 v[146:147], off
	v_lshl_add_u64 v[146:147], s[36:37], 0, v[140:141]
	s_add_i32 m0, s31, 0xe000
	s_nop 0
	global_load_lds_dwordx4 v[146:147], off
	s_waitcnt vmcnt(8)
	s_waitcnt lgkmcnt(0)
	s_barrier
	s_setprio 1
	s_waitcnt lgkmcnt(0)
	v_mfma_f32_16x16x32_bf16 v[126:129], v[154:157], v[186:189], v[126:129]
	v_mfma_f32_16x16x32_bf16 v[122:125], v[162:165], v[186:189], v[122:125]
	v_mfma_f32_16x16x32_bf16 v[118:121], v[154:157], v[194:197], v[118:121]
	v_mfma_f32_16x16x32_bf16 v[110:113], v[162:165], v[194:197], v[110:113]
	v_mfma_f32_16x16x32_bf16 v[102:105], v[154:157], v[202:205], v[102:105]
	v_mfma_f32_16x16x32_bf16 v[94:97], v[162:165], v[202:205], v[94:97]
	v_mfma_f32_16x16x32_bf16 v[86:89], v[154:157], v[210:213], v[86:89]
	v_mfma_f32_16x16x32_bf16 v[78:81], v[162:165], v[210:213], v[78:81]
	v_mfma_f32_16x16x32_bf16 v[126:129], v[158:161], v[190:193], v[126:129]
	v_mfma_f32_16x16x32_bf16 v[122:125], v[166:169], v[190:193], v[122:125]
	v_mfma_f32_16x16x32_bf16 v[118:121], v[158:161], v[198:201], v[118:121]
	v_mfma_f32_16x16x32_bf16 v[110:113], v[166:169], v[198:201], v[110:113]
	v_mfma_f32_16x16x32_bf16 v[102:105], v[158:161], v[206:209], v[102:105]
	v_mfma_f32_16x16x32_bf16 v[94:97], v[166:169], v[206:209], v[94:97]
	v_mfma_f32_16x16x32_bf16 v[86:89], v[158:161], v[214:217], v[86:89]
	v_mfma_f32_16x16x32_bf16 v[78:81], v[166:169], v[214:217], v[78:81]
	v_mfma_f32_16x16x32_bf16 v[114:117], v[170:173], v[186:189], v[114:117]
	v_mfma_f32_16x16x32_bf16 v[106:109], v[178:181], v[186:189], v[106:109]
	v_mfma_f32_16x16x32_bf16 v[98:101], v[170:173], v[194:197], v[98:101]
	v_mfma_f32_16x16x32_bf16 v[90:93], v[178:181], v[194:197], v[90:93]
	v_mfma_f32_16x16x32_bf16 v[82:85], v[170:173], v[202:205], v[82:85]
	v_mfma_f32_16x16x32_bf16 v[74:77], v[178:181], v[202:205], v[74:77]
	v_mfma_f32_16x16x32_bf16 v[70:73], v[170:173], v[210:213], v[70:73]
	v_mfma_f32_16x16x32_bf16 v[66:69], v[178:181], v[210:213], v[66:69]
	v_mfma_f32_16x16x32_bf16 v[114:117], v[174:177], v[190:193], v[114:117]
	v_mfma_f32_16x16x32_bf16 v[106:109], v[182:185], v[190:193], v[106:109]
	v_mfma_f32_16x16x32_bf16 v[98:101], v[174:177], v[198:201], v[98:101]
	v_mfma_f32_16x16x32_bf16 v[90:93], v[182:185], v[198:201], v[90:93]
	v_mfma_f32_16x16x32_bf16 v[82:85], v[174:177], v[206:209], v[82:85]
	v_mfma_f32_16x16x32_bf16 v[74:77], v[182:185], v[206:209], v[74:77]
	v_mfma_f32_16x16x32_bf16 v[70:73], v[174:177], v[214:217], v[70:73]
	v_mfma_f32_16x16x32_bf16 v[66:69], v[182:185], v[214:217], v[66:69]
	s_setprio 0
	s_barrier
	s_add_i32 s65, s51, s15
	v_lshl_add_u64 v[146:147], s[40:41], 0, v[132:133]
	s_mov_b32 m0, s65
	ds_read_b128 v[186:189], v152 offset:16384
	ds_read_b128 v[190:193], v152 offset:17408
	ds_read_b128 v[194:197], v152 offset:18432
	ds_read_b128 v[198:201], v152 offset:19456
	ds_read_b128 v[202:205], v152 offset:20480
	ds_read_b128 v[206:209], v152 offset:21504
	ds_read_b128 v[210:213], v152 offset:22528
	ds_read_b128 v[214:217], v152 offset:23552
	global_load_lds_dwordx4 v[146:147], off
	s_add_i32 m0, s65, 0x2000
	s_add_u32 s66, s40, 0x100000
	v_lshl_add_u64 v[218:219], s[40:41], 0, v[136:137]
	s_addc_u32 s67, s41, 0
	s_add_i32 s65, s52, s15
	global_load_lds_dwordx4 v[218:219], off
	v_lshl_add_u64 v[220:221], s[66:67], 0, v[132:133]
	s_mov_b32 m0, s65
	v_lshl_add_u64 v[222:223], s[42:43], 0, v[134:135]
	global_load_lds_dwordx4 v[220:221], off
	v_lshl_add_u64 v[220:221], s[66:67], 0, v[136:137]
	s_add_i32 m0, s65, 0x2000
	s_nop 0
	global_load_lds_dwordx4 v[220:221], off
	v_lshl_add_u64 v[220:221], s[42:43], 0, v[130:131]
	s_mov_b32 m0, s31
	s_nop 0
	global_load_lds_dwordx4 v[220:221], off
	s_mov_b32 m0, s44
	s_nop 0
	global_load_lds_dwordx4 v[222:223], off
	s_waitcnt vmcnt(8)
	s_waitcnt lgkmcnt(0)
	s_barrier
	s_setprio 1
	s_waitcnt lgkmcnt(0)
	v_mfma_f32_16x16x32_bf16 v[62:65], v[154:157], v[186:189], v[62:65]
	v_mfma_f32_16x16x32_bf16 v[58:61], v[162:165], v[186:189], v[58:61]
	v_mfma_f32_16x16x32_bf16 v[54:57], v[154:157], v[194:197], v[54:57]
	v_mfma_f32_16x16x32_bf16 v[46:49], v[162:165], v[194:197], v[46:49]
	v_mfma_f32_16x16x32_bf16 v[38:41], v[154:157], v[202:205], v[38:41]
	v_mfma_f32_16x16x32_bf16 v[30:33], v[162:165], v[202:205], v[30:33]
	v_mfma_f32_16x16x32_bf16 v[22:25], v[154:157], v[210:213], v[22:25]
	v_mfma_f32_16x16x32_bf16 v[14:17], v[162:165], v[210:213], v[14:17]
	v_mfma_f32_16x16x32_bf16 v[62:65], v[158:161], v[190:193], v[62:65]
	v_mfma_f32_16x16x32_bf16 v[58:61], v[166:169], v[190:193], v[58:61]
	v_mfma_f32_16x16x32_bf16 v[54:57], v[158:161], v[198:201], v[54:57]
	v_mfma_f32_16x16x32_bf16 v[46:49], v[166:169], v[198:201], v[46:49]
	v_mfma_f32_16x16x32_bf16 v[38:41], v[158:161], v[206:209], v[38:41]
	v_mfma_f32_16x16x32_bf16 v[30:33], v[166:169], v[206:209], v[30:33]
	v_mfma_f32_16x16x32_bf16 v[22:25], v[158:161], v[214:217], v[22:25]
	v_mfma_f32_16x16x32_bf16 v[14:17], v[166:169], v[214:217], v[14:17]
	v_mfma_f32_16x16x32_bf16 v[50:53], v[170:173], v[186:189], v[50:53]
	v_mfma_f32_16x16x32_bf16 v[42:45], v[178:181], v[186:189], v[42:45]
	v_mfma_f32_16x16x32_bf16 v[34:37], v[170:173], v[194:197], v[34:37]
	v_mfma_f32_16x16x32_bf16 v[26:29], v[178:181], v[194:197], v[26:29]
	v_mfma_f32_16x16x32_bf16 v[18:21], v[170:173], v[202:205], v[18:21]
	v_mfma_f32_16x16x32_bf16 v[10:13], v[178:181], v[202:205], v[10:13]
	v_mfma_f32_16x16x32_bf16 v[6:9], v[170:173], v[210:213], v[6:9]
	v_mfma_f32_16x16x32_bf16 v[2:5], v[178:181], v[210:213], v[2:5]
	v_mfma_f32_16x16x32_bf16 v[50:53], v[174:177], v[190:193], v[50:53]
	v_mfma_f32_16x16x32_bf16 v[42:45], v[182:185], v[190:193], v[42:45]
	v_mfma_f32_16x16x32_bf16 v[34:37], v[174:177], v[198:201], v[34:37]
	v_mfma_f32_16x16x32_bf16 v[26:29], v[182:185], v[198:201], v[26:29]
	v_mfma_f32_16x16x32_bf16 v[18:21], v[174:177], v[206:209], v[18:21]
	v_mfma_f32_16x16x32_bf16 v[10:13], v[182:185], v[206:209], v[10:13]
	v_mfma_f32_16x16x32_bf16 v[6:9], v[174:177], v[214:217], v[6:9]
	v_mfma_f32_16x16x32_bf16 v[2:5], v[182:185], v[214:217], v[2:5]
	s_setprio 0
	s_barrier
	s_add_i32 s65, 0, 0x18000
	v_add_u32_e32 v153, s65, v148
	s_add_i32 s66, 0, 0x1c000
	ds_read_b128 v[154:157], v153
	ds_read_b128 v[158:161], v153 offset:1024
	ds_read_b128 v[162:165], v153 offset:2048
	ds_read_b128 v[166:169], v153 offset:3072
	v_add_u32_e32 v153, s66, v148
	ds_read_b128 v[170:173], v153
	ds_read_b128 v[174:177], v153 offset:1024
	ds_read_b128 v[178:181], v153 offset:2048
	ds_read_b128 v[182:185], v153 offset:3072
	s_add_u32 s42, s42, 0x100000
	s_addc_u32 s43, s43, 0
	s_mov_b32 m0, s45
	v_lshl_add_u64 v[224:225], s[42:43], 0, v[130:131]
	ds_read_b128 v[186:189], v152 offset:32768
	ds_read_b128 v[190:193], v152 offset:33792
	ds_read_b128 v[194:197], v152 offset:34816
	ds_read_b128 v[198:201], v152 offset:35840
	ds_read_b128 v[202:205], v152 offset:36864
	ds_read_b128 v[206:209], v152 offset:37888
	ds_read_b128 v[210:213], v152 offset:38912
	ds_read_b128 v[214:217], v152 offset:39936
	global_load_lds_dwordx4 v[224:225], off
	v_lshl_add_u64 v[224:225], s[42:43], 0, v[134:135]
	s_mov_b32 m0, s46
	s_nop 0
	global_load_lds_dwordx4 v[224:225], off
	s_waitcnt vmcnt(8)
	s_waitcnt lgkmcnt(0)
	s_barrier
	s_setprio 1
	s_waitcnt lgkmcnt(0)
	v_mfma_f32_16x16x32_bf16 v[126:129], v[154:157], v[186:189], v[126:129]
	v_mfma_f32_16x16x32_bf16 v[122:125], v[162:165], v[186:189], v[122:125]
	v_mfma_f32_16x16x32_bf16 v[118:121], v[154:157], v[194:197], v[118:121]
	v_mfma_f32_16x16x32_bf16 v[110:113], v[162:165], v[194:197], v[110:113]
	v_mfma_f32_16x16x32_bf16 v[102:105], v[154:157], v[202:205], v[102:105]
	v_mfma_f32_16x16x32_bf16 v[94:97], v[162:165], v[202:205], v[94:97]
	v_mfma_f32_16x16x32_bf16 v[86:89], v[154:157], v[210:213], v[86:89]
	v_mfma_f32_16x16x32_bf16 v[78:81], v[162:165], v[210:213], v[78:81]
	v_mfma_f32_16x16x32_bf16 v[126:129], v[158:161], v[190:193], v[126:129]
	v_mfma_f32_16x16x32_bf16 v[122:125], v[166:169], v[190:193], v[122:125]
	v_mfma_f32_16x16x32_bf16 v[118:121], v[158:161], v[198:201], v[118:121]
	v_mfma_f32_16x16x32_bf16 v[110:113], v[166:169], v[198:201], v[110:113]
	v_mfma_f32_16x16x32_bf16 v[102:105], v[158:161], v[206:209], v[102:105]
	v_mfma_f32_16x16x32_bf16 v[94:97], v[166:169], v[206:209], v[94:97]
	v_mfma_f32_16x16x32_bf16 v[86:89], v[158:161], v[214:217], v[86:89]
	v_mfma_f32_16x16x32_bf16 v[78:81], v[166:169], v[214:217], v[78:81]
	v_mfma_f32_16x16x32_bf16 v[114:117], v[170:173], v[186:189], v[114:117]
	v_mfma_f32_16x16x32_bf16 v[106:109], v[178:181], v[186:189], v[106:109]
	v_mfma_f32_16x16x32_bf16 v[98:101], v[170:173], v[194:197], v[98:101]
	v_mfma_f32_16x16x32_bf16 v[90:93], v[178:181], v[194:197], v[90:93]
	v_mfma_f32_16x16x32_bf16 v[82:85], v[170:173], v[202:205], v[82:85]
	v_mfma_f32_16x16x32_bf16 v[74:77], v[178:181], v[202:205], v[74:77]
	v_mfma_f32_16x16x32_bf16 v[70:73], v[170:173], v[210:213], v[70:73]
	v_mfma_f32_16x16x32_bf16 v[66:69], v[178:181], v[210:213], v[66:69]
	v_mfma_f32_16x16x32_bf16 v[114:117], v[174:177], v[190:193], v[114:117]
	v_mfma_f32_16x16x32_bf16 v[106:109], v[182:185], v[190:193], v[106:109]
	v_mfma_f32_16x16x32_bf16 v[98:101], v[174:177], v[198:201], v[98:101]
	v_mfma_f32_16x16x32_bf16 v[90:93], v[182:185], v[198:201], v[90:93]
	v_mfma_f32_16x16x32_bf16 v[82:85], v[174:177], v[206:209], v[82:85]
	v_mfma_f32_16x16x32_bf16 v[74:77], v[182:185], v[206:209], v[74:77]
	v_mfma_f32_16x16x32_bf16 v[70:73], v[174:177], v[214:217], v[70:73]
	v_mfma_f32_16x16x32_bf16 v[66:69], v[182:185], v[214:217], v[66:69]
	s_setprio 0
	s_barrier
	s_add_i32 s42, s65, s15
	v_lshl_add_u64 v[146:147], v[146:147], 0, s[10:11]
	s_mov_b32 m0, s42
	ds_read_b128 v[186:189], v152 offset:49152
	ds_read_b128 v[190:193], v152 offset:50176
	ds_read_b128 v[194:197], v152 offset:51200
	ds_read_b128 v[198:201], v152 offset:52224
	ds_read_b128 v[202:205], v152 offset:53248
	ds_read_b128 v[206:209], v152 offset:54272
	ds_read_b128 v[210:213], v152 offset:55296
	ds_read_b128 v[214:217], v152 offset:56320
	global_load_lds_dwordx4 v[146:147], off
	s_add_i32 m0, s42, 0x2000
	s_add_u32 s40, s40, 0x100080
	v_lshl_add_u64 v[146:147], v[218:219], 0, s[10:11]
	s_addc_u32 s41, s41, 0
	s_add_i32 s42, s66, s15
	global_load_lds_dwordx4 v[146:147], off
	v_lshl_add_u64 v[146:147], s[40:41], 0, v[132:133]
	s_mov_b32 m0, s42
	s_nop 0
	global_load_lds_dwordx4 v[146:147], off
	v_lshl_add_u64 v[146:147], s[40:41], 0, v[136:137]
	s_add_i32 m0, s42, 0x2000
	s_nop 0
	global_load_lds_dwordx4 v[146:147], off
	v_lshl_add_u64 v[146:147], v[220:221], 0, s[10:11]
	s_mov_b32 m0, s48
	s_nop 0
	global_load_lds_dwordx4 v[146:147], off
	v_lshl_add_u64 v[146:147], v[222:223], 0, s[10:11]
	s_mov_b32 m0, s49
	s_nop 0
	global_load_lds_dwordx4 v[146:147], off
	s_waitcnt vmcnt(8)
	s_waitcnt lgkmcnt(0)
	s_barrier
	s_setprio 1
	s_waitcnt lgkmcnt(0)
	v_mfma_f32_16x16x32_bf16 v[62:65], v[154:157], v[186:189], v[62:65]
	v_mfma_f32_16x16x32_bf16 v[58:61], v[162:165], v[186:189], v[58:61]
	v_mfma_f32_16x16x32_bf16 v[54:57], v[154:157], v[194:197], v[54:57]
	v_mfma_f32_16x16x32_bf16 v[46:49], v[162:165], v[194:197], v[46:49]
	v_mfma_f32_16x16x32_bf16 v[38:41], v[154:157], v[202:205], v[38:41]
	v_mfma_f32_16x16x32_bf16 v[30:33], v[162:165], v[202:205], v[30:33]
	v_mfma_f32_16x16x32_bf16 v[22:25], v[154:157], v[210:213], v[22:25]
	v_mfma_f32_16x16x32_bf16 v[14:17], v[162:165], v[210:213], v[14:17]
	v_mfma_f32_16x16x32_bf16 v[62:65], v[158:161], v[190:193], v[62:65]
	v_mfma_f32_16x16x32_bf16 v[58:61], v[166:169], v[190:193], v[58:61]
	v_mfma_f32_16x16x32_bf16 v[54:57], v[158:161], v[198:201], v[54:57]
	v_mfma_f32_16x16x32_bf16 v[46:49], v[166:169], v[198:201], v[46:49]
	v_mfma_f32_16x16x32_bf16 v[38:41], v[158:161], v[206:209], v[38:41]
	v_mfma_f32_16x16x32_bf16 v[30:33], v[166:169], v[206:209], v[30:33]
	v_mfma_f32_16x16x32_bf16 v[22:25], v[158:161], v[214:217], v[22:25]
	v_mfma_f32_16x16x32_bf16 v[14:17], v[166:169], v[214:217], v[14:17]
	v_mfma_f32_16x16x32_bf16 v[50:53], v[170:173], v[186:189], v[50:53]
	v_mfma_f32_16x16x32_bf16 v[42:45], v[178:181], v[186:189], v[42:45]
	v_mfma_f32_16x16x32_bf16 v[34:37], v[170:173], v[194:197], v[34:37]
	v_mfma_f32_16x16x32_bf16 v[26:29], v[178:181], v[194:197], v[26:29]
	v_mfma_f32_16x16x32_bf16 v[18:21], v[170:173], v[202:205], v[18:21]
	v_mfma_f32_16x16x32_bf16 v[10:13], v[178:181], v[202:205], v[10:13]
	v_mfma_f32_16x16x32_bf16 v[6:9], v[170:173], v[210:213], v[6:9]
	v_mfma_f32_16x16x32_bf16 v[2:5], v[178:181], v[210:213], v[2:5]
	v_mfma_f32_16x16x32_bf16 v[50:53], v[174:177], v[190:193], v[50:53]
	v_mfma_f32_16x16x32_bf16 v[42:45], v[182:185], v[190:193], v[42:45]
	v_mfma_f32_16x16x32_bf16 v[34:37], v[174:177], v[198:201], v[34:37]
	v_mfma_f32_16x16x32_bf16 v[26:29], v[182:185], v[198:201], v[26:29]
	v_mfma_f32_16x16x32_bf16 v[18:21], v[174:177], v[206:209], v[18:21]
	v_mfma_f32_16x16x32_bf16 v[10:13], v[182:185], v[206:209], v[10:13]
	v_mfma_f32_16x16x32_bf16 v[6:9], v[174:177], v[214:217], v[6:9]
	v_mfma_f32_16x16x32_bf16 v[2:5], v[182:185], v[214:217], v[2:5]
	s_setprio 0
	s_barrier
	s_add_i32 s64, s64, 2
	s_add_u32 s36, s36, 0x100
	s_addc_u32 s37, s37, 0
	s_add_u32 s62, s62, 0x100
	s_addc_u32 s63, s63, 0
	s_cmp_gt_u32 s64, 61
	s_cbranch_scc0 .LBB0_1211
	s_and_b64 vcc, exec, s[12:13]
	s_cbranch_vccz .LBB0_1214
	s_barrier

.LBB0_1337:
	ds_read_b128 v[154:157], v151
	ds_read_b128 v[158:161], v151 offset:1024
	ds_read_b128 v[162:165], v151 offset:2048
	ds_read_b128 v[166:169], v151 offset:3072
	ds_read_b128 v[170:173], v152
	ds_read_b128 v[174:177], v152 offset:1024
	ds_read_b128 v[178:181], v152 offset:2048
	ds_read_b128 v[182:185], v152 offset:3072
	s_add_u32 s26, s24, 0xfff00080
	s_addc_u32 s27, s25, -1
	s_cmp_eq_u32 s53, 60
	s_cselect_b32 s29, s17, s27
	s_cselect_b32 s28, s49, s26
	s_cselect_b32 s27, s13, s52
	s_cselect_b32 s26, s50, s51
	v_lshl_add_u64 v[146:147], s[24:25], 0, v[138:139]
	s_add_i32 m0, s23, 0xc000
	ds_read_b128 v[186:189], v153
	ds_read_b128 v[190:193], v153 offset:1024
	ds_read_b128 v[194:197], v153 offset:2048
	ds_read_b128 v[198:201], v153 offset:3072
	ds_read_b128 v[202:205], v153 offset:4096
	ds_read_b128 v[206:209], v153 offset:5120
	ds_read_b128 v[210:213], v153 offset:6144
	ds_read_b128 v[214:217], v153 offset:7168
	global_load_lds_dwordx4 v[146:147], off
	v_lshl_add_u64 v[146:147], s[24:25], 0, v[140:141]
	s_add_i32 m0, s23, 0xe000
	s_nop 0
	global_load_lds_dwordx4 v[146:147], off
	s_waitcnt vmcnt(8)
	s_waitcnt lgkmcnt(0)
	s_barrier
	s_setprio 1
	s_waitcnt lgkmcnt(0)
	v_mfma_f32_16x16x32_bf16 v[126:129], v[154:157], v[186:189], v[126:129]
	v_mfma_f32_16x16x32_bf16 v[122:125], v[162:165], v[186:189], v[122:125]
	v_mfma_f32_16x16x32_bf16 v[110:113], v[154:157], v[194:197], v[110:113]
	v_mfma_f32_16x16x32_bf16 v[106:109], v[162:165], v[194:197], v[106:109]
	v_mfma_f32_16x16x32_bf16 v[94:97], v[154:157], v[202:205], v[94:97]
	v_mfma_f32_16x16x32_bf16 v[90:93], v[162:165], v[202:205], v[90:93]
	v_mfma_f32_16x16x32_bf16 v[78:81], v[154:157], v[210:213], v[78:81]
	v_mfma_f32_16x16x32_bf16 v[74:77], v[162:165], v[210:213], v[74:77]
	v_mfma_f32_16x16x32_bf16 v[126:129], v[158:161], v[190:193], v[126:129]
	v_mfma_f32_16x16x32_bf16 v[122:125], v[166:169], v[190:193], v[122:125]
	v_mfma_f32_16x16x32_bf16 v[110:113], v[158:161], v[198:201], v[110:113]
	v_mfma_f32_16x16x32_bf16 v[106:109], v[166:169], v[198:201], v[106:109]
	v_mfma_f32_16x16x32_bf16 v[94:97], v[158:161], v[206:209], v[94:97]
	v_mfma_f32_16x16x32_bf16 v[90:93], v[166:169], v[206:209], v[90:93]
	v_mfma_f32_16x16x32_bf16 v[78:81], v[158:161], v[214:217], v[78:81]
	v_mfma_f32_16x16x32_bf16 v[74:77], v[166:169], v[214:217], v[74:77]
	v_mfma_f32_16x16x32_bf16 v[118:121], v[170:173], v[186:189], v[118:121]
	v_mfma_f32_16x16x32_bf16 v[114:117], v[178:181], v[186:189], v[114:117]
	v_mfma_f32_16x16x32_bf16 v[102:105], v[170:173], v[194:197], v[102:105]
	v_mfma_f32_16x16x32_bf16 v[98:101], v[178:181], v[194:197], v[98:101]
	v_mfma_f32_16x16x32_bf16 v[86:89], v[170:173], v[202:205], v[86:89]
	v_mfma_f32_16x16x32_bf16 v[82:85], v[178:181], v[202:205], v[82:85]
	v_mfma_f32_16x16x32_bf16 v[70:73], v[170:173], v[210:213], v[70:73]
	v_mfma_f32_16x16x32_bf16 v[66:69], v[178:181], v[210:213], v[66:69]
	v_mfma_f32_16x16x32_bf16 v[118:121], v[174:177], v[190:193], v[118:121]
	v_mfma_f32_16x16x32_bf16 v[114:117], v[182:185], v[190:193], v[114:117]
	v_mfma_f32_16x16x32_bf16 v[102:105], v[174:177], v[198:201], v[102:105]
	v_mfma_f32_16x16x32_bf16 v[98:101], v[182:185], v[198:201], v[98:101]
	v_mfma_f32_16x16x32_bf16 v[86:89], v[174:177], v[206:209], v[86:89]
	v_mfma_f32_16x16x32_bf16 v[82:85], v[182:185], v[206:209], v[82:85]
	v_mfma_f32_16x16x32_bf16 v[70:73], v[174:177], v[214:217], v[70:73]
	v_mfma_f32_16x16x32_bf16 v[66:69], v[182:185], v[214:217], v[66:69]
	s_setprio 0
	s_barrier
	s_add_i32 s54, s45, s15
	v_lshl_add_u64 v[146:147], s[26:27], 0, v[134:135]
	s_mov_b32 m0, s54
	ds_read_b128 v[186:189], v153 offset:16384
	ds_read_b128 v[190:193], v153 offset:17408
	ds_read_b128 v[194:197], v153 offset:18432
	ds_read_b128 v[198:201], v153 offset:19456
	ds_read_b128 v[202:205], v153 offset:20480
	ds_read_b128 v[206:209], v153 offset:21504
	ds_read_b128 v[210:213], v153 offset:22528
	ds_read_b128 v[214:217], v153 offset:23552
	global_load_lds_dwordx4 v[146:147], off
	s_add_i32 m0, s54, 0x2000
	s_add_u32 s54, s26, 0x100000
	v_lshl_add_u64 v[218:219], s[26:27], 0, v[130:131]
	s_addc_u32 s55, s27, 0
	s_add_i32 s56, s46, s15
	global_load_lds_dwordx4 v[218:219], off
	v_lshl_add_u64 v[220:221], s[54:55], 0, v[134:135]
	s_mov_b32 m0, s56
	v_lshl_add_u64 v[222:223], s[28:29], 0, v[132:133]
	global_load_lds_dwordx4 v[220:221], off
	v_lshl_add_u64 v[220:221], s[54:55], 0, v[130:131]
	s_add_i32 m0, s56, 0x2000
	s_nop 0
	global_load_lds_dwordx4 v[220:221], off
	v_lshl_add_u64 v[220:221], s[28:29], 0, v[136:137]
	s_mov_b32 m0, s23
	s_nop 0
	global_load_lds_dwordx4 v[220:221], off
	s_mov_b32 m0, s36
	s_nop 0
	global_load_lds_dwordx4 v[222:223], off
	s_waitcnt vmcnt(8)
	s_waitcnt lgkmcnt(0)
	s_barrier
	s_setprio 1
	s_waitcnt lgkmcnt(0)
	v_mfma_f32_16x16x32_bf16 v[62:65], v[154:157], v[186:189], v[62:65]
	v_mfma_f32_16x16x32_bf16 v[58:61], v[162:165], v[186:189], v[58:61]
	v_mfma_f32_16x16x32_bf16 v[46:49], v[154:157], v[194:197], v[46:49]
	v_mfma_f32_16x16x32_bf16 v[42:45], v[162:165], v[194:197], v[42:45]
	v_mfma_f32_16x16x32_bf16 v[30:33], v[154:157], v[202:205], v[30:33]
	v_mfma_f32_16x16x32_bf16 v[26:29], v[162:165], v[202:205], v[26:29]
	v_mfma_f32_16x16x32_bf16 v[14:17], v[154:157], v[210:213], v[14:17]
	v_mfma_f32_16x16x32_bf16 v[10:13], v[162:165], v[210:213], v[10:13]
	v_mfma_f32_16x16x32_bf16 v[62:65], v[158:161], v[190:193], v[62:65]
	v_mfma_f32_16x16x32_bf16 v[58:61], v[166:169], v[190:193], v[58:61]
	v_mfma_f32_16x16x32_bf16 v[46:49], v[158:161], v[198:201], v[46:49]
	v_mfma_f32_16x16x32_bf16 v[42:45], v[166:169], v[198:201], v[42:45]
	v_mfma_f32_16x16x32_bf16 v[30:33], v[158:161], v[206:209], v[30:33]
	v_mfma_f32_16x16x32_bf16 v[26:29], v[166:169], v[206:209], v[26:29]
	v_mfma_f32_16x16x32_bf16 v[14:17], v[158:161], v[214:217], v[14:17]
	v_mfma_f32_16x16x32_bf16 v[10:13], v[166:169], v[214:217], v[10:13]
	v_mfma_f32_16x16x32_bf16 v[54:57], v[170:173], v[186:189], v[54:57]
	v_mfma_f32_16x16x32_bf16 v[50:53], v[178:181], v[186:189], v[50:53]
	v_mfma_f32_16x16x32_bf16 v[38:41], v[170:173], v[194:197], v[38:41]
	v_mfma_f32_16x16x32_bf16 v[34:37], v[178:181], v[194:197], v[34:37]
	v_mfma_f32_16x16x32_bf16 v[22:25], v[170:173], v[202:205], v[22:25]
	v_mfma_f32_16x16x32_bf16 v[18:21], v[178:181], v[202:205], v[18:21]
	v_mfma_f32_16x16x32_bf16 v[6:9], v[170:173], v[210:213], v[6:9]
	v_mfma_f32_16x16x32_bf16 v[2:5], v[178:181], v[210:213], v[2:5]
	v_mfma_f32_16x16x32_bf16 v[54:57], v[174:177], v[190:193], v[54:57]
	v_mfma_f32_16x16x32_bf16 v[50:53], v[182:185], v[190:193], v[50:53]
	v_mfma_f32_16x16x32_bf16 v[38:41], v[174:177], v[198:201], v[38:41]
	v_mfma_f32_16x16x32_bf16 v[34:37], v[182:185], v[198:201], v[34:37]
	v_mfma_f32_16x16x32_bf16 v[22:25], v[174:177], v[206:209], v[22:25]
	v_mfma_f32_16x16x32_bf16 v[18:21], v[182:185], v[206:209], v[18:21]
	v_mfma_f32_16x16x32_bf16 v[6:9], v[174:177], v[214:217], v[6:9]
	v_mfma_f32_16x16x32_bf16 v[2:5], v[182:185], v[214:217], v[2:5]
	s_setprio 0
	s_barrier
	s_add_i32 s54, 0, 0x18000
	s_add_i32 s55, 0, 0x1c000
	v_add_u32_e32 v166, s54, v149
	v_add_u32_e32 v182, s55, v149
	ds_read_b128 v[154:157], v166
	ds_read_b128 v[158:161], v166 offset:1024
	ds_read_b128 v[162:165], v166 offset:2048
	ds_read_b128 v[166:169], v166 offset:3072
	ds_read_b128 v[170:173], v182
	ds_read_b128 v[174:177], v182 offset:1024
	ds_read_b128 v[178:181], v182 offset:2048
	ds_read_b128 v[182:185], v182 offset:3072
	s_add_u32 s28, s28, 0x100000
	s_addc_u32 s29, s29, 0
	s_mov_b32 m0, s37
	v_lshl_add_u64 v[224:225], s[28:29], 0, v[136:137]
	ds_read_b128 v[186:189], v153 offset:32768
	ds_read_b128 v[190:193], v153 offset:33792
	ds_read_b128 v[194:197], v153 offset:34816
	ds_read_b128 v[198:201], v153 offset:35840
	ds_read_b128 v[202:205], v153 offset:36864
	ds_read_b128 v[206:209], v153 offset:37888
	ds_read_b128 v[210:213], v153 offset:38912
	ds_read_b128 v[214:217], v153 offset:39936
	global_load_lds_dwordx4 v[224:225], off
	v_lshl_add_u64 v[224:225], s[28:29], 0, v[132:133]
	s_mov_b32 m0, s40
	s_nop 0
	global_load_lds_dwordx4 v[224:225], off
	s_waitcnt vmcnt(8)
	s_waitcnt lgkmcnt(0)
	s_barrier
	s_setprio 1
	s_waitcnt lgkmcnt(0)
	v_mfma_f32_16x16x32_bf16 v[126:129], v[154:157], v[186:189], v[126:129]
	v_mfma_f32_16x16x32_bf16 v[122:125], v[162:165], v[186:189], v[122:125]
	v_mfma_f32_16x16x32_bf16 v[110:113], v[154:157], v[194:197], v[110:113]
	v_mfma_f32_16x16x32_bf16 v[106:109], v[162:165], v[194:197], v[106:109]
	v_mfma_f32_16x16x32_bf16 v[94:97], v[154:157], v[202:205], v[94:97]
	v_mfma_f32_16x16x32_bf16 v[90:93], v[162:165], v[202:205], v[90:93]
	v_mfma_f32_16x16x32_bf16 v[78:81], v[154:157], v[210:213], v[78:81]
	v_mfma_f32_16x16x32_bf16 v[74:77], v[162:165], v[210:213], v[74:77]
	v_mfma_f32_16x16x32_bf16 v[126:129], v[158:161], v[190:193], v[126:129]
	v_mfma_f32_16x16x32_bf16 v[122:125], v[166:169], v[190:193], v[122:125]
	v_mfma_f32_16x16x32_bf16 v[110:113], v[158:161], v[198:201], v[110:113]
	v_mfma_f32_16x16x32_bf16 v[106:109], v[166:169], v[198:201], v[106:109]
	v_mfma_f32_16x16x32_bf16 v[94:97], v[158:161], v[206:209], v[94:97]
	v_mfma_f32_16x16x32_bf16 v[90:93], v[166:169], v[206:209], v[90:93]
	v_mfma_f32_16x16x32_bf16 v[78:81], v[158:161], v[214:217], v[78:81]
	v_mfma_f32_16x16x32_bf16 v[74:77], v[166:169], v[214:217], v[74:77]
	v_mfma_f32_16x16x32_bf16 v[118:121], v[170:173], v[186:189], v[118:121]
	v_mfma_f32_16x16x32_bf16 v[114:117], v[178:181], v[186:189], v[114:117]
	v_mfma_f32_16x16x32_bf16 v[102:105], v[170:173], v[194:197], v[102:105]
	v_mfma_f32_16x16x32_bf16 v[98:101], v[178:181], v[194:197], v[98:101]
	v_mfma_f32_16x16x32_bf16 v[86:89], v[170:173], v[202:205], v[86:89]
	v_mfma_f32_16x16x32_bf16 v[82:85], v[178:181], v[202:205], v[82:85]
	v_mfma_f32_16x16x32_bf16 v[70:73], v[170:173], v[210:213], v[70:73]
	v_mfma_f32_16x16x32_bf16 v[66:69], v[178:181], v[210:213], v[66:69]
	v_mfma_f32_16x16x32_bf16 v[118:121], v[174:177], v[190:193], v[118:121]
	v_mfma_f32_16x16x32_bf16 v[114:117], v[182:185], v[190:193], v[114:117]
	v_mfma_f32_16x16x32_bf16 v[102:105], v[174:177], v[198:201], v[102:105]
	v_mfma_f32_16x16x32_bf16 v[98:101], v[182:185], v[198:201], v[98:101]
	v_mfma_f32_16x16x32_bf16 v[86:89], v[174:177], v[206:209], v[86:89]
	v_mfma_f32_16x16x32_bf16 v[82:85], v[182:185], v[206:209], v[82:85]
	v_mfma_f32_16x16x32_bf16 v[70:73], v[174:177], v[214:217], v[70:73]
	v_mfma_f32_16x16x32_bf16 v[66:69], v[182:185], v[214:217], v[66:69]
	s_setprio 0
	s_barrier
	s_add_i32 s28, s54, s15
	v_lshl_add_u64 v[146:147], v[146:147], 0, s[8:9]
	s_mov_b32 m0, s28
	ds_read_b128 v[186:189], v153 offset:49152
	ds_read_b128 v[190:193], v153 offset:50176
	ds_read_b128 v[194:197], v153 offset:51200
	ds_read_b128 v[198:201], v153 offset:52224
	ds_read_b128 v[202:205], v153 offset:53248
	ds_read_b128 v[206:209], v153 offset:54272
	ds_read_b128 v[210:213], v153 offset:55296
	ds_read_b128 v[214:217], v153 offset:56320
	global_load_lds_dwordx4 v[146:147], off
	s_add_i32 m0, s28, 0x2000
	s_add_u32 s26, s26, 0x100080
	v_lshl_add_u64 v[146:147], v[218:219], 0, s[8:9]
	s_addc_u32 s27, s27, 0
	s_add_i32 s28, s55, s15
	global_load_lds_dwordx4 v[146:147], off
	v_lshl_add_u64 v[146:147], s[26:27], 0, v[134:135]
	s_mov_b32 m0, s28
	s_nop 0
	global_load_lds_dwordx4 v[146:147], off
	v_lshl_add_u64 v[146:147], s[26:27], 0, v[130:131]
	s_add_i32 m0, s28, 0x2000
	s_nop 0
	global_load_lds_dwordx4 v[146:147], off
	v_lshl_add_u64 v[146:147], v[220:221], 0, s[8:9]
	s_mov_b32 m0, s42
	s_nop 0
	global_load_lds_dwordx4 v[146:147], off
	v_lshl_add_u64 v[146:147], v[222:223], 0, s[8:9]
	s_mov_b32 m0, s43
	s_nop 0
	global_load_lds_dwordx4 v[146:147], off
	s_waitcnt vmcnt(8)
	s_waitcnt lgkmcnt(0)
	s_barrier
	s_setprio 1
	s_waitcnt lgkmcnt(0)
	v_mfma_f32_16x16x32_bf16 v[62:65], v[154:157], v[186:189], v[62:65]
	v_mfma_f32_16x16x32_bf16 v[58:61], v[162:165], v[186:189], v[58:61]
	v_mfma_f32_16x16x32_bf16 v[46:49], v[154:157], v[194:197], v[46:49]
	v_mfma_f32_16x16x32_bf16 v[42:45], v[162:165], v[194:197], v[42:45]
	v_mfma_f32_16x16x32_bf16 v[30:33], v[154:157], v[202:205], v[30:33]
	v_mfma_f32_16x16x32_bf16 v[26:29], v[162:165], v[202:205], v[26:29]
	v_mfma_f32_16x16x32_bf16 v[14:17], v[154:157], v[210:213], v[14:17]
	v_mfma_f32_16x16x32_bf16 v[10:13], v[162:165], v[210:213], v[10:13]
	v_mfma_f32_16x16x32_bf16 v[62:65], v[158:161], v[190:193], v[62:65]
	v_mfma_f32_16x16x32_bf16 v[58:61], v[166:169], v[190:193], v[58:61]
	v_mfma_f32_16x16x32_bf16 v[46:49], v[158:161], v[198:201], v[46:49]
	v_mfma_f32_16x16x32_bf16 v[42:45], v[166:169], v[198:201], v[42:45]
	v_mfma_f32_16x16x32_bf16 v[30:33], v[158:161], v[206:209], v[30:33]
	v_mfma_f32_16x16x32_bf16 v[26:29], v[166:169], v[206:209], v[26:29]
	v_mfma_f32_16x16x32_bf16 v[14:17], v[158:161], v[214:217], v[14:17]
	v_mfma_f32_16x16x32_bf16 v[10:13], v[166:169], v[214:217], v[10:13]
	v_mfma_f32_16x16x32_bf16 v[54:57], v[170:173], v[186:189], v[54:57]
	v_mfma_f32_16x16x32_bf16 v[50:53], v[178:181], v[186:189], v[50:53]
	v_mfma_f32_16x16x32_bf16 v[38:41], v[170:173], v[194:197], v[38:41]
	v_mfma_f32_16x16x32_bf16 v[34:37], v[178:181], v[194:197], v[34:37]
	v_mfma_f32_16x16x32_bf16 v[22:25], v[170:173], v[202:205], v[22:25]
	v_mfma_f32_16x16x32_bf16 v[18:21], v[178:181], v[202:205], v[18:21]
	v_mfma_f32_16x16x32_bf16 v[6:9], v[170:173], v[210:213], v[6:9]
	v_mfma_f32_16x16x32_bf16 v[2:5], v[178:181], v[210:213], v[2:5]
	v_mfma_f32_16x16x32_bf16 v[54:57], v[174:177], v[190:193], v[54:57]
	v_mfma_f32_16x16x32_bf16 v[50:53], v[182:185], v[190:193], v[50:53]
	v_mfma_f32_16x16x32_bf16 v[38:41], v[174:177], v[198:201], v[38:41]
	v_mfma_f32_16x16x32_bf16 v[34:37], v[182:185], v[198:201], v[34:37]
	v_mfma_f32_16x16x32_bf16 v[22:25], v[174:177], v[206:209], v[22:25]
	v_mfma_f32_16x16x32_bf16 v[18:21], v[182:185], v[206:209], v[18:21]
	v_mfma_f32_16x16x32_bf16 v[6:9], v[174:177], v[214:217], v[6:9]
	v_mfma_f32_16x16x32_bf16 v[2:5], v[182:185], v[214:217], v[2:5]
	s_setprio 0
	s_barrier
	s_add_i32 s53, s53, 2
	s_add_u32 s24, s24, 0x100
	s_addc_u32 s25, s25, 0
	s_add_u32 s51, s51, 0x100
	s_addc_u32 s52, s52, 0
	s_cmp_gt_u32 s53, 61
	s_cbranch_scc0 .LBB0_1337
	s_and_b64 vcc, exec, s[10:11]
	s_cbranch_vccz .LBB0_1340
	s_barrier

.LBB0_1434:
	ds_read_b128 v[154:157], v150
	ds_read_b128 v[158:161], v150 offset:1024
	ds_read_b128 v[162:165], v150 offset:2048
	ds_read_b128 v[166:169], v150 offset:3072
	ds_read_b128 v[170:173], v151
	ds_read_b128 v[174:177], v151 offset:1024
	ds_read_b128 v[178:181], v151 offset:2048
	ds_read_b128 v[182:185], v151 offset:3072
	s_add_u32 s30, s28, 0x100
	s_addc_u32 s31, s29, 0
	s_cmpk_eq_i32 s66, 0xa8
	s_cselect_b32 s41, s5, s31
	s_cselect_b32 s40, s4, s30
	s_cselect_b32 s37, s27, s65
	s_cselect_b32 s36, s26, s64
	v_lshl_add_u64 v[146:147], s[28:29], 0, v[138:139]
	s_add_i32 m0, s15, 0xc000
	ds_read_b128 v[186:189], v152
	ds_read_b128 v[190:193], v152 offset:1024
	ds_read_b128 v[194:197], v152 offset:2048
	ds_read_b128 v[198:201], v152 offset:3072
	ds_read_b128 v[202:205], v152 offset:4096
	ds_read_b128 v[206:209], v152 offset:5120
	ds_read_b128 v[210:213], v152 offset:6144
	ds_read_b128 v[214:217], v152 offset:7168
	global_load_lds_dwordx4 v[146:147], off
	v_lshl_add_u64 v[146:147], s[28:29], 0, v[140:141]
	s_add_i32 m0, s15, 0xe000
	s_nop 0
	global_load_lds_dwordx4 v[146:147], off
	s_waitcnt vmcnt(8)
	s_waitcnt lgkmcnt(0)
	s_barrier
	s_setprio 1
	s_waitcnt lgkmcnt(0)
	v_mfma_f32_16x16x32_bf16 v[126:129], v[154:157], v[186:189], v[126:129]
	v_mfma_f32_16x16x32_bf16 v[122:125], v[162:165], v[186:189], v[122:125]
	v_mfma_f32_16x16x32_bf16 v[118:121], v[154:157], v[194:197], v[118:121]
	v_mfma_f32_16x16x32_bf16 v[110:113], v[162:165], v[194:197], v[110:113]
	v_mfma_f32_16x16x32_bf16 v[102:105], v[154:157], v[202:205], v[102:105]
	v_mfma_f32_16x16x32_bf16 v[94:97], v[162:165], v[202:205], v[94:97]
	v_mfma_f32_16x16x32_bf16 v[86:89], v[154:157], v[210:213], v[86:89]
	v_mfma_f32_16x16x32_bf16 v[78:81], v[162:165], v[210:213], v[78:81]
	v_mfma_f32_16x16x32_bf16 v[126:129], v[158:161], v[190:193], v[126:129]
	v_mfma_f32_16x16x32_bf16 v[122:125], v[166:169], v[190:193], v[122:125]
	v_mfma_f32_16x16x32_bf16 v[118:121], v[158:161], v[198:201], v[118:121]
	v_mfma_f32_16x16x32_bf16 v[110:113], v[166:169], v[198:201], v[110:113]
	v_mfma_f32_16x16x32_bf16 v[102:105], v[158:161], v[206:209], v[102:105]
	v_mfma_f32_16x16x32_bf16 v[94:97], v[166:169], v[206:209], v[94:97]
	v_mfma_f32_16x16x32_bf16 v[86:89], v[158:161], v[214:217], v[86:89]
	v_mfma_f32_16x16x32_bf16 v[78:81], v[166:169], v[214:217], v[78:81]
	v_mfma_f32_16x16x32_bf16 v[114:117], v[170:173], v[186:189], v[114:117]
	v_mfma_f32_16x16x32_bf16 v[106:109], v[178:181], v[186:189], v[106:109]
	v_mfma_f32_16x16x32_bf16 v[98:101], v[170:173], v[194:197], v[98:101]
	v_mfma_f32_16x16x32_bf16 v[90:93], v[178:181], v[194:197], v[90:93]
	v_mfma_f32_16x16x32_bf16 v[82:85], v[170:173], v[202:205], v[82:85]
	v_mfma_f32_16x16x32_bf16 v[74:77], v[178:181], v[202:205], v[74:77]
	v_mfma_f32_16x16x32_bf16 v[70:73], v[170:173], v[210:213], v[70:73]
	v_mfma_f32_16x16x32_bf16 v[66:69], v[178:181], v[210:213], v[66:69]
	v_mfma_f32_16x16x32_bf16 v[114:117], v[174:177], v[190:193], v[114:117]
	v_mfma_f32_16x16x32_bf16 v[106:109], v[182:185], v[190:193], v[106:109]
	v_mfma_f32_16x16x32_bf16 v[98:101], v[174:177], v[198:201], v[98:101]
	v_mfma_f32_16x16x32_bf16 v[90:93], v[182:185], v[198:201], v[90:93]
	v_mfma_f32_16x16x32_bf16 v[82:85], v[174:177], v[206:209], v[82:85]
	v_mfma_f32_16x16x32_bf16 v[74:77], v[182:185], v[206:209], v[74:77]
	v_mfma_f32_16x16x32_bf16 v[70:73], v[174:177], v[214:217], v[70:73]
	v_mfma_f32_16x16x32_bf16 v[66:69], v[182:185], v[214:217], v[66:69]
	s_setprio 0
	s_barrier
	s_add_i32 s28, s52, s3
	v_lshl_add_u64 v[146:147], s[36:37], 0, v[132:133]
	s_mov_b32 m0, s28
	ds_read_b128 v[186:189], v152 offset:16384
	ds_read_b128 v[190:193], v152 offset:17408
	ds_read_b128 v[194:197], v152 offset:18432
	ds_read_b128 v[198:201], v152 offset:19456
	ds_read_b128 v[202:205], v152 offset:20480
	ds_read_b128 v[206:209], v152 offset:21504
	ds_read_b128 v[210:213], v152 offset:22528
	ds_read_b128 v[214:217], v152 offset:23552
	global_load_lds_dwordx4 v[146:147], off
	s_add_i32 m0, s28, 0x2000
	s_add_u32 s28, s36, 0x2b0000
	v_lshl_add_u64 v[218:219], s[36:37], 0, v[136:137]
	s_addc_u32 s29, s37, 0
	s_add_i32 s67, s53, s3
	global_load_lds_dwordx4 v[218:219], off
	v_lshl_add_u64 v[220:221], s[28:29], 0, v[132:133]
	s_mov_b32 m0, s67
	v_lshl_add_u64 v[222:223], s[40:41], 0, v[134:135]
	global_load_lds_dwordx4 v[220:221], off
	v_lshl_add_u64 v[220:221], s[28:29], 0, v[136:137]
	s_add_i32 m0, s67, 0x2000
	s_nop 0
	global_load_lds_dwordx4 v[220:221], off
	v_lshl_add_u64 v[220:221], s[40:41], 0, v[130:131]
	s_mov_b32 m0, s15
	s_nop 0
	global_load_lds_dwordx4 v[220:221], off
	s_mov_b32 m0, s42
	s_nop 0
	global_load_lds_dwordx4 v[222:223], off
	s_waitcnt vmcnt(8)
	s_waitcnt lgkmcnt(0)
	s_barrier
	s_setprio 1
	s_waitcnt lgkmcnt(0)
	v_mfma_f32_16x16x32_bf16 v[62:65], v[154:157], v[186:189], v[62:65]
	v_mfma_f32_16x16x32_bf16 v[58:61], v[162:165], v[186:189], v[58:61]
	v_mfma_f32_16x16x32_bf16 v[54:57], v[154:157], v[194:197], v[54:57]
	v_mfma_f32_16x16x32_bf16 v[46:49], v[162:165], v[194:197], v[46:49]
	v_mfma_f32_16x16x32_bf16 v[38:41], v[154:157], v[202:205], v[38:41]
	v_mfma_f32_16x16x32_bf16 v[30:33], v[162:165], v[202:205], v[30:33]
	v_mfma_f32_16x16x32_bf16 v[22:25], v[154:157], v[210:213], v[22:25]
	v_mfma_f32_16x16x32_bf16 v[14:17], v[162:165], v[210:213], v[14:17]
	v_mfma_f32_16x16x32_bf16 v[62:65], v[158:161], v[190:193], v[62:65]
	v_mfma_f32_16x16x32_bf16 v[58:61], v[166:169], v[190:193], v[58:61]
	v_mfma_f32_16x16x32_bf16 v[54:57], v[158:161], v[198:201], v[54:57]
	v_mfma_f32_16x16x32_bf16 v[46:49], v[166:169], v[198:201], v[46:49]
	v_mfma_f32_16x16x32_bf16 v[38:41], v[158:161], v[206:209], v[38:41]
	v_mfma_f32_16x16x32_bf16 v[30:33], v[166:169], v[206:209], v[30:33]
	v_mfma_f32_16x16x32_bf16 v[22:25], v[158:161], v[214:217], v[22:25]
	v_mfma_f32_16x16x32_bf16 v[14:17], v[166:169], v[214:217], v[14:17]
	v_mfma_f32_16x16x32_bf16 v[50:53], v[170:173], v[186:189], v[50:53]
	v_mfma_f32_16x16x32_bf16 v[42:45], v[178:181], v[186:189], v[42:45]
	v_mfma_f32_16x16x32_bf16 v[34:37], v[170:173], v[194:197], v[34:37]
	v_mfma_f32_16x16x32_bf16 v[26:29], v[178:181], v[194:197], v[26:29]
	v_mfma_f32_16x16x32_bf16 v[18:21], v[170:173], v[202:205], v[18:21]
	v_mfma_f32_16x16x32_bf16 v[10:13], v[178:181], v[202:205], v[10:13]
	v_mfma_f32_16x16x32_bf16 v[6:9], v[170:173], v[210:213], v[6:9]
	v_mfma_f32_16x16x32_bf16 v[2:5], v[178:181], v[210:213], v[2:5]
	v_mfma_f32_16x16x32_bf16 v[50:53], v[174:177], v[190:193], v[50:53]
	v_mfma_f32_16x16x32_bf16 v[42:45], v[182:185], v[190:193], v[42:45]
	v_mfma_f32_16x16x32_bf16 v[34:37], v[174:177], v[198:201], v[34:37]
	v_mfma_f32_16x16x32_bf16 v[26:29], v[182:185], v[198:201], v[26:29]
	v_mfma_f32_16x16x32_bf16 v[18:21], v[174:177], v[206:209], v[18:21]
	v_mfma_f32_16x16x32_bf16 v[10:13], v[182:185], v[206:209], v[10:13]
	v_mfma_f32_16x16x32_bf16 v[6:9], v[174:177], v[214:217], v[6:9]
	v_mfma_f32_16x16x32_bf16 v[2:5], v[182:185], v[214:217], v[2:5]
	s_setprio 0
	s_barrier
	s_add_i32 s67, 0, 0x18000
	v_add_u32_e32 v153, s67, v148
	s_add_i32 s68, 0, 0x1c000
	ds_read_b128 v[154:157], v153
	ds_read_b128 v[158:161], v153 offset:1024
	ds_read_b128 v[162:165], v153 offset:2048
	ds_read_b128 v[166:169], v153 offset:3072
	v_add_u32_e32 v153, s68, v148
	ds_read_b128 v[170:173], v153
	ds_read_b128 v[174:177], v153 offset:1024
	ds_read_b128 v[178:181], v153 offset:2048
	ds_read_b128 v[182:185], v153 offset:3072
	s_add_u32 s28, s40, 0x2b0000
	s_addc_u32 s29, s41, 0
	s_mov_b32 m0, s43
	v_lshl_add_u64 v[224:225], s[28:29], 0, v[130:131]
	ds_read_b128 v[186:189], v152 offset:32768
	ds_read_b128 v[190:193], v152 offset:33792
	ds_read_b128 v[194:197], v152 offset:34816
	ds_read_b128 v[198:201], v152 offset:35840
	ds_read_b128 v[202:205], v152 offset:36864
	ds_read_b128 v[206:209], v152 offset:37888
	ds_read_b128 v[210:213], v152 offset:38912
	ds_read_b128 v[214:217], v152 offset:39936
	global_load_lds_dwordx4 v[224:225], off
	v_lshl_add_u64 v[224:225], s[28:29], 0, v[134:135]
	s_mov_b32 m0, s44
	s_nop 0
	global_load_lds_dwordx4 v[224:225], off
	s_waitcnt vmcnt(8)
	s_waitcnt lgkmcnt(0)
	s_barrier
	s_setprio 1
	s_waitcnt lgkmcnt(0)
	v_mfma_f32_16x16x32_bf16 v[126:129], v[154:157], v[186:189], v[126:129]
	v_mfma_f32_16x16x32_bf16 v[122:125], v[162:165], v[186:189], v[122:125]
	v_mfma_f32_16x16x32_bf16 v[118:121], v[154:157], v[194:197], v[118:121]
	v_mfma_f32_16x16x32_bf16 v[110:113], v[162:165], v[194:197], v[110:113]
	v_mfma_f32_16x16x32_bf16 v[102:105], v[154:157], v[202:205], v[102:105]
	v_mfma_f32_16x16x32_bf16 v[94:97], v[162:165], v[202:205], v[94:97]
	v_mfma_f32_16x16x32_bf16 v[86:89], v[154:157], v[210:213], v[86:89]
	v_mfma_f32_16x16x32_bf16 v[78:81], v[162:165], v[210:213], v[78:81]
	v_mfma_f32_16x16x32_bf16 v[126:129], v[158:161], v[190:193], v[126:129]
	v_mfma_f32_16x16x32_bf16 v[122:125], v[166:169], v[190:193], v[122:125]
	v_mfma_f32_16x16x32_bf16 v[118:121], v[158:161], v[198:201], v[118:121]
	v_mfma_f32_16x16x32_bf16 v[110:113], v[166:169], v[198:201], v[110:113]
	v_mfma_f32_16x16x32_bf16 v[102:105], v[158:161], v[206:209], v[102:105]
	v_mfma_f32_16x16x32_bf16 v[94:97], v[166:169], v[206:209], v[94:97]
	v_mfma_f32_16x16x32_bf16 v[86:89], v[158:161], v[214:217], v[86:89]
	v_mfma_f32_16x16x32_bf16 v[78:81], v[166:169], v[214:217], v[78:81]
	v_mfma_f32_16x16x32_bf16 v[114:117], v[170:173], v[186:189], v[114:117]
	v_mfma_f32_16x16x32_bf16 v[106:109], v[178:181], v[186:189], v[106:109]
	v_mfma_f32_16x16x32_bf16 v[98:101], v[170:173], v[194:197], v[98:101]
	v_mfma_f32_16x16x32_bf16 v[90:93], v[178:181], v[194:197], v[90:93]
	v_mfma_f32_16x16x32_bf16 v[82:85], v[170:173], v[202:205], v[82:85]
	v_mfma_f32_16x16x32_bf16 v[74:77], v[178:181], v[202:205], v[74:77]
	v_mfma_f32_16x16x32_bf16 v[70:73], v[170:173], v[210:213], v[70:73]
	v_mfma_f32_16x16x32_bf16 v[66:69], v[178:181], v[210:213], v[66:69]
	v_mfma_f32_16x16x32_bf16 v[114:117], v[174:177], v[190:193], v[114:117]
	v_mfma_f32_16x16x32_bf16 v[106:109], v[182:185], v[190:193], v[106:109]
	v_mfma_f32_16x16x32_bf16 v[98:101], v[174:177], v[198:201], v[98:101]
	v_mfma_f32_16x16x32_bf16 v[90:93], v[182:185], v[198:201], v[90:93]
	v_mfma_f32_16x16x32_bf16 v[82:85], v[174:177], v[206:209], v[82:85]
	v_mfma_f32_16x16x32_bf16 v[74:77], v[182:185], v[206:209], v[74:77]
	v_mfma_f32_16x16x32_bf16 v[70:73], v[174:177], v[214:217], v[70:73]
	v_mfma_f32_16x16x32_bf16 v[66:69], v[182:185], v[214:217], v[66:69]
	s_setprio 0
	s_barrier
	s_add_i32 s28, s67, s3
	v_lshl_add_u64 v[146:147], v[146:147], 0, s[12:13]
	s_mov_b32 m0, s28
	ds_read_b128 v[186:189], v152 offset:49152
	ds_read_b128 v[190:193], v152 offset:50176
	ds_read_b128 v[194:197], v152 offset:51200
	ds_read_b128 v[198:201], v152 offset:52224
	ds_read_b128 v[202:205], v152 offset:53248
	ds_read_b128 v[206:209], v152 offset:54272
	ds_read_b128 v[210:213], v152 offset:55296
	ds_read_b128 v[214:217], v152 offset:56320
	global_load_lds_dwordx4 v[146:147], off
	s_add_i32 m0, s28, 0x2000
	s_add_u32 s28, s36, 0x2b0080
	v_lshl_add_u64 v[146:147], v[218:219], 0, s[12:13]
	s_addc_u32 s29, s37, 0
	s_add_i32 s36, s68, s3
	global_load_lds_dwordx4 v[146:147], off
	v_lshl_add_u64 v[146:147], s[28:29], 0, v[132:133]
	s_mov_b32 m0, s36
	s_nop 0
	global_load_lds_dwordx4 v[146:147], off
	v_lshl_add_u64 v[146:147], s[28:29], 0, v[136:137]
	s_add_i32 m0, s36, 0x2000
	s_nop 0
	global_load_lds_dwordx4 v[146:147], off
	v_lshl_add_u64 v[146:147], v[220:221], 0, s[12:13]
	s_mov_b32 m0, s46
	s_nop 0
	global_load_lds_dwordx4 v[146:147], off
	v_lshl_add_u64 v[146:147], v[222:223], 0, s[12:13]
	s_mov_b32 m0, s47
	s_nop 0
	global_load_lds_dwordx4 v[146:147], off
	s_waitcnt vmcnt(8)
	s_waitcnt lgkmcnt(0)
	s_barrier
	s_setprio 1
	s_waitcnt lgkmcnt(0)
	v_mfma_f32_16x16x32_bf16 v[62:65], v[154:157], v[186:189], v[62:65]
	v_mfma_f32_16x16x32_bf16 v[58:61], v[162:165], v[186:189], v[58:61]
	v_mfma_f32_16x16x32_bf16 v[54:57], v[154:157], v[194:197], v[54:57]
	v_mfma_f32_16x16x32_bf16 v[46:49], v[162:165], v[194:197], v[46:49]
	v_mfma_f32_16x16x32_bf16 v[38:41], v[154:157], v[202:205], v[38:41]
	v_mfma_f32_16x16x32_bf16 v[30:33], v[162:165], v[202:205], v[30:33]
	v_mfma_f32_16x16x32_bf16 v[22:25], v[154:157], v[210:213], v[22:25]
	v_mfma_f32_16x16x32_bf16 v[14:17], v[162:165], v[210:213], v[14:17]
	v_mfma_f32_16x16x32_bf16 v[62:65], v[158:161], v[190:193], v[62:65]
	v_mfma_f32_16x16x32_bf16 v[58:61], v[166:169], v[190:193], v[58:61]
	v_mfma_f32_16x16x32_bf16 v[54:57], v[158:161], v[198:201], v[54:57]
	v_mfma_f32_16x16x32_bf16 v[46:49], v[166:169], v[198:201], v[46:49]
	v_mfma_f32_16x16x32_bf16 v[38:41], v[158:161], v[206:209], v[38:41]
	v_mfma_f32_16x16x32_bf16 v[30:33], v[166:169], v[206:209], v[30:33]
	v_mfma_f32_16x16x32_bf16 v[22:25], v[158:161], v[214:217], v[22:25]
	v_mfma_f32_16x16x32_bf16 v[14:17], v[166:169], v[214:217], v[14:17]
	v_mfma_f32_16x16x32_bf16 v[50:53], v[170:173], v[186:189], v[50:53]
	v_mfma_f32_16x16x32_bf16 v[42:45], v[178:181], v[186:189], v[42:45]
	v_mfma_f32_16x16x32_bf16 v[34:37], v[170:173], v[194:197], v[34:37]
	v_mfma_f32_16x16x32_bf16 v[26:29], v[178:181], v[194:197], v[26:29]
	v_mfma_f32_16x16x32_bf16 v[18:21], v[170:173], v[202:205], v[18:21]
	v_mfma_f32_16x16x32_bf16 v[10:13], v[178:181], v[202:205], v[10:13]
	v_mfma_f32_16x16x32_bf16 v[6:9], v[170:173], v[210:213], v[6:9]
	v_mfma_f32_16x16x32_bf16 v[2:5], v[178:181], v[210:213], v[2:5]
	v_mfma_f32_16x16x32_bf16 v[50:53], v[174:177], v[190:193], v[50:53]
	v_mfma_f32_16x16x32_bf16 v[42:45], v[182:185], v[190:193], v[42:45]
	v_mfma_f32_16x16x32_bf16 v[34:37], v[174:177], v[198:201], v[34:37]
	v_mfma_f32_16x16x32_bf16 v[26:29], v[182:185], v[198:201], v[26:29]
	v_mfma_f32_16x16x32_bf16 v[18:21], v[174:177], v[206:209], v[18:21]
	v_mfma_f32_16x16x32_bf16 v[10:13], v[182:185], v[206:209], v[10:13]
	v_mfma_f32_16x16x32_bf16 v[6:9], v[174:177], v[214:217], v[6:9]
	v_mfma_f32_16x16x32_bf16 v[2:5], v[182:185], v[214:217], v[2:5]
	s_setprio 0
	s_barrier
	s_add_i32 s66, s66, 2
	s_add_u32 s64, s64, 0x100
	s_addc_u32 s65, s65, 0
	s_cmpk_gt_u32 s66, 0xa9
	s_mov_b64 s[28:29], s[30:31]
	s_cbranch_scc0 .LBB0_1434
	s_and_b64 vcc, exec, s[16:17]
	s_cbranch_vccz .LBB0_1437
	s_barrier
